# FoX loop: K key tiles loaded HBM->LDS directly (9 lane-linear wave blocks of the padded image, chunk g -> row g/9)
# baseline (speedup 1.0000x reference)
.LBB0_654:
	v_lshlrev_b32_e32 v16, 3, v18
	v_lshrrev_b32_e32 v14, 2, v19
	v_lshlrev_b32_e32 v15, 1, v18
	v_and_b32_e32 v16, 24, v16
	v_and_or_b32 v15, v15, 32, v16
	v_and_or_b32 v14, v14, 3, v156
	v_lshl_or_b32 v14, v14, 6, v15
	v_lshl_add_u64 v[136:137], v[12:13], 1, s[12:13]
	s_add_i32 s12, s10, 2
	v_mul_u32_u24_e32 v164, 0x90, v20
	v_lshl_add_u64 v[138:139], v[144:145], 1, s[14:15]
	s_cmp_ge_i32 s12, s35
	v_add_u32_e32 v158, 0, v30
	v_add_u32_e32 v159, 0, v14
	s_barrier
	s_lshl_b32 s34, s33, 10
	s_add_i32 s39, s34, 0x3400
	s_add_i32 s38, s34, 0xf000
	s_cmp_eq_u32 s33, 0
	s_cselect_b32 s38, 0x2000, s38
	v_mbcnt_lo_u32_b32 v119, -1, 0
	v_mbcnt_hi_u32_b32 v119, -1, v119
	v_lshl_or_b32 v121, s33, 6, v119
	v_lshrrev_b32_e32 v118, 3, v121
	v_lshlrev_b32_e32 v118, 10, v118
	v_and_b32_e32 v114, 7, v121
	v_lshl_add_u32 v118, v114, 4, v118
	v_add_u32_e32 v115, 0x200, v119
	v_mul_u32_u24_e32 v114, 0x1c72, v115
	v_lshrrev_b32_e32 v114, 16, v114
	v_mul_u32_u24_e32 v116, 9, v114
	v_sub_u32_e32 v116, v115, v116
	v_min_u32_e32 v116, 7, v116
	v_lshlrev_b32_e32 v114, 10, v114
	v_lshl_add_u32 v114, v116, 4, v114
	v_sub_u32_e32 v114, v114, v118
	v_ashrrev_i32_e32 v115, 31, v114
	v_mul_u32_u24_e32 v120, 0x1c72, v121
	v_lshrrev_b32_e32 v120, 16, v120
	v_mul_u32_u24_e32 v116, 9, v120
	v_sub_u32_e32 v116, v121, v116
	v_min_u32_e32 v116, 7, v116
	v_lshlrev_b32_e32 v120, 10, v120
	v_lshl_add_u32 v120, v116, 4, v120
	v_sub_u32_e32 v120, v120, v118
	v_ashrrev_i32_e32 v121, 31, v120
	v_readfirstlane_b32 s54, v155
	s_add_i32 s55, s54, 0x8800
	s_add_i32 s54, s54, 0x6800
	v_add_u32_e32 v218, v164, v30
	s_and_b32 s12, s33, 1
	s_lshl_b32 s12, s12, 5
	v_lshlrev_b32_e32 v219, 2, v21
	v_sub_u32_e32 v219, v20, v219
	v_add_u32_e32 v219, s12, v219
	s_lshr_b32 s11, s33, 1
	v_mov_b32_e32 v14, 0
	v_mov_b32_e32 v15, 0
	v_mov_b32_e32 v16, 0
	v_mov_b32_e32 v17, 0
	v_mov_b32_e32 v18, 0
	v_mov_b32_e32 v19, 0
	v_mov_b32_e32 v20, 0
	v_mov_b32_e32 v21, 0
	v_mov_b32_e32 v22, 0
	v_mov_b32_e32 v23, 0
	v_mov_b32_e32 v24, 0
	v_mov_b32_e32 v25, 0
	v_mov_b32_e32 v26, 0
	v_mov_b32_e32 v27, 0
	v_mov_b32_e32 v28, 0
	v_mov_b32_e32 v29, 0
	v_mov_b32_e32 v30, 0
	v_mov_b32_e32 v31, 0
	v_mov_b32_e32 v32, 0
	v_mov_b32_e32 v33, 0
	v_mov_b32_e32 v34, 0
	v_mov_b32_e32 v35, 0
	v_mov_b32_e32 v36, 0
	v_mov_b32_e32 v37, 0
	v_mov_b32_e32 v38, 0
	v_mov_b32_e32 v39, 0
	v_mov_b32_e32 v40, 0
	v_mov_b32_e32 v41, 0
	v_mov_b32_e32 v42, 0
	v_mov_b32_e32 v43, 0
	v_mov_b32_e32 v44, 0
	v_mov_b32_e32 v45, 0
	v_mov_b32_e32 v161, 0
	v_mov_b32_e32 v160, 0xf149f2ca
	s_add_i32 s12, s10, 2
	s_ashr_i32 s13, s12, 31
	s_lshl_b64 s[14:15], s[12:13], 16
	v_lshl_add_u64 v[244:245], v[136:137], 0, s[14:15]
	v_lshl_add_u64 v[116:117], v[244:245], 0, v[114:115]
	v_lshl_add_u64 v[244:245], v[244:245], 0, v[120:121]
	s_lshl_b64 s[14:15], s[12:13], 8
	v_mov_b32_e32 v141, 0
	v_lshl_add_u64 v[250:251], s[4:5], 0, v[140:141]
	v_lshl_add_u64 v[250:251], v[250:251], 0, s[14:15]
	s_add_i32 s12, s10, 1
	s_ashr_i32 s13, s12, 31
	s_lshl_b64 s[14:15], s[12:13], 16
	v_lshl_add_u64 v[248:249], v[138:139], 0, s[14:15]
	s_mov_b32 m0, s34
	s_nop 0
	global_load_lds_dwordx4 v[244:245], off
	s_mov_b32 m0, s38
	s_nop 0
	global_load_lds_dwordx4 v[116:117], off
	s_and_saveexec_b64 s[12:13], s[6:7]
	s_cbranch_execz .Lf3_nockp
	global_load_dword v152, v[250:251], off
.Lf3_nockp:
	s_or_b64 exec, exec, s[12:13]
	s_mov_b32 m0, s55
	s_nop 0
	global_load_lds_dwordx4 v[248:249], off
	s_mov_b64 s[14:15], 0x10000
	v_lshl_add_u64 v[242:243], v[244:245], 0, s[14:15]
	v_lshl_add_u64 v[114:115], v[116:117], 0, s[14:15]
	v_lshl_add_u64 v[244:245], v[242:243], 0, s[14:15]
	v_lshl_add_u64 v[116:117], v[114:115], 0, s[14:15]
	v_lshl_add_u64 v[246:247], v[248:249], 0, s[14:15]
	v_lshl_add_u64 v[248:249], v[246:247], 0, s[14:15]
	s_mov_b64 s[14:15], 0x100
	v_lshl_add_u64 v[250:251], v[250:251], 0, s[14:15]
	ds_read_b128 v[78:81], v158 offset:43264
	ds_read_b128 v[82:85], v158 offset:43296
	ds_read_b128 v[86:89], v158 offset:43328
	ds_read_b128 v[90:93], v158 offset:43360
	ds_read_b128 v[94:97], v158 offset:43392
	ds_read_b128 v[98:101], v158 offset:43424
	ds_read_b128 v[102:105], v158 offset:43456
	ds_read_b128 v[106:109], v158 offset:43488
	s_waitcnt lgkmcnt(4)
	ds_read_b128 v[190:193], v218 offset:13312
	ds_read_b128 v[194:197], v218 offset:17920
	ds_read_b128 v[198:201], v218 offset:13344
	ds_read_b128 v[202:205], v218 offset:17952
	ds_read_b128 v[206:209], v218 offset:13376
	ds_read_b128 v[210:213], v218 offset:17984
	ds_read_b128 v[214:217], v218 offset:13408
	ds_read_b128 v[222:225], v218 offset:18016
	v_max3_f32 v124, v46, v47, v48
	v_max3_f32 v125, v49, v50, v51
	v_max3_f32 v124, v124, v52, v53
	v_max3_f32 v125, v125, v54, v55
	v_max3_f32 v124, v124, v56, v57
	v_max3_f32 v125, v125, v58, v59
	v_max3_f32 v124, v124, v60, v61
	v_max3_f32 v125, v125, v62, v63
	v_max3_f32 v124, v124, v64, v65
	v_max3_f32 v125, v125, v66, v67
	v_max3_f32 v124, v124, v68, v69
	v_max3_f32 v125, v125, v70, v71
	v_max3_f32 v124, v124, v72, v73
	v_max3_f32 v125, v125, v74, v75
	v_max3_f32 v124, v124, v76, v77
	v_max_f32_e32 v124, v124, v125
	v_mov_b32_e32 v125, v124
	s_nop 1
	v_permlane32_swap_b32_e32 v124, v125
	v_max_f32_e32 v126, v124, v125
	s_add_i32 s12, s10, 6
	s_cmp_lt_i32 s12, s41
	s_cbranch_scc1 .Lf3_loop
	s_add_i32 s12, s10, 4
	s_cmp_lt_i32 s12, s41
	s_cbranch_scc1 .Lf3_tail0
	s_branch .Lf3_tail2

.Lf3_resc_reta:
	s_waitcnt lgkmcnt(7)
	v_mfma_f32_32x32x16_bf16 v[78:93], v[190:193], v[0:3], v[78:93]
	ds_read_b64_tr_b16 v[190:191], v159 offset:26624
	ds_read_b64_tr_b16 v[192:193], v159 offset:27136
	v_sub_f32_e32 v46, v46, v160
	v_sub_f32_e32 v47, v47, v160
	v_sub_f32_e32 v48, v48, v160
	v_sub_f32_e32 v49, v49, v160
	v_sub_f32_e32 v50, v50, v160
	v_sub_f32_e32 v51, v51, v160
	v_sub_f32_e32 v52, v52, v160
	v_sub_f32_e32 v53, v53, v160
	v_exp_f32_e32 v46, v46
	v_exp_f32_e32 v47, v47
	v_exp_f32_e32 v48, v48
	v_exp_f32_e32 v49, v49
	s_waitcnt lgkmcnt(8)
	v_mfma_f32_32x32x16_bf16 v[94:109], v[194:197], v[0:3], v[94:109]
	ds_read_b64_tr_b16 v[194:195], v159 offset:30720
	ds_read_b64_tr_b16 v[196:197], v159 offset:31232
	v_exp_f32_e32 v50, v50
	v_exp_f32_e32 v51, v51
	v_exp_f32_e32 v52, v52
	v_exp_f32_e32 v53, v53
	v_add_f32_e32 v122, v46, v47
	v_add_f32_e32 v123, v48, v49
	v_add_f32_e32 v122, v122, v50
	v_add_f32_e32 v123, v123, v51
	v_add_f32_e32 v122, v122, v52
	v_add_f32_e32 v123, v123, v53
	v_cvt_pk_bf16_f32 v226, v46, v47
	v_cvt_pk_bf16_f32 v227, v48, v49
	s_waitcnt lgkmcnt(9)
	v_mfma_f32_32x32x16_bf16 v[78:93], v[198:201], v[4:7], v[78:93]
	ds_read_b64_tr_b16 v[198:199], v159 offset:27648
	ds_read_b64_tr_b16 v[200:201], v159 offset:28160
	v_cvt_pk_bf16_f32 v228, v50, v51
	v_cvt_pk_bf16_f32 v229, v52, v53
	v_sub_f32_e32 v54, v54, v160
	v_sub_f32_e32 v55, v55, v160
	v_sub_f32_e32 v56, v56, v160
	v_sub_f32_e32 v57, v57, v160
	v_sub_f32_e32 v58, v58, v160
	v_sub_f32_e32 v59, v59, v160
	v_sub_f32_e32 v60, v60, v160
	v_sub_f32_e32 v61, v61, v160
	v_exp_f32_e32 v54, v54
	s_waitcnt lgkmcnt(10)
	v_mfma_f32_32x32x16_bf16 v[94:109], v[202:205], v[4:7], v[94:109]
	ds_read_b64_tr_b16 v[202:203], v159 offset:31744
	ds_read_b64_tr_b16 v[204:205], v159 offset:32256
	v_exp_f32_e32 v55, v55
	v_exp_f32_e32 v56, v56
	v_exp_f32_e32 v57, v57
	v_exp_f32_e32 v58, v58
	v_exp_f32_e32 v59, v59
	v_exp_f32_e32 v60, v60
	v_exp_f32_e32 v61, v61
	v_add_f32_e32 v122, v122, v54
	v_add_f32_e32 v123, v123, v55
	v_add_f32_e32 v122, v122, v56
	v_add_f32_e32 v123, v123, v57
	s_waitcnt lgkmcnt(11)
	v_mfma_f32_32x32x16_bf16 v[78:93], v[206:209], v[8:11], v[78:93]
	ds_read_b64_tr_b16 v[206:207], v159 offset:28672
	ds_read_b64_tr_b16 v[208:209], v159 offset:29184
	v_add_f32_e32 v122, v122, v58
	v_add_f32_e32 v123, v123, v59
	v_add_f32_e32 v122, v122, v60
	v_add_f32_e32 v123, v123, v61
	v_cvt_pk_bf16_f32 v230, v54, v55
	v_cvt_pk_bf16_f32 v231, v56, v57
	v_cvt_pk_bf16_f32 v232, v58, v59
	v_cvt_pk_bf16_f32 v233, v60, v61
	v_sub_f32_e32 v62, v62, v160
	v_sub_f32_e32 v63, v63, v160
	v_sub_f32_e32 v64, v64, v160
	s_waitcnt lgkmcnt(12)
	v_mfma_f32_32x32x16_bf16 v[94:109], v[210:213], v[8:11], v[94:109]
	ds_read_b64_tr_b16 v[210:211], v159 offset:32768
	ds_read_b64_tr_b16 v[212:213], v159 offset:33280
	v_sub_f32_e32 v65, v65, v160
	v_sub_f32_e32 v66, v66, v160
	v_sub_f32_e32 v67, v67, v160
	v_sub_f32_e32 v68, v68, v160
	v_sub_f32_e32 v69, v69, v160
	v_exp_f32_e32 v62, v62
	v_exp_f32_e32 v63, v63
	v_exp_f32_e32 v64, v64
	v_exp_f32_e32 v65, v65
	v_exp_f32_e32 v66, v66
	v_exp_f32_e32 v67, v67
	s_waitcnt lgkmcnt(13)
	v_mfma_f32_32x32x16_bf16 v[78:93], v[214:217], v[110:113], v[78:93]
	ds_read_b64_tr_b16 v[214:215], v159 offset:29696
	ds_read_b64_tr_b16 v[216:217], v159 offset:30208
	v_exp_f32_e32 v68, v68
	v_exp_f32_e32 v69, v69
	v_add_f32_e32 v122, v122, v62
	v_add_f32_e32 v123, v123, v63
	v_add_f32_e32 v122, v122, v64
	v_add_f32_e32 v123, v123, v65
	v_add_f32_e32 v122, v122, v66
	v_add_f32_e32 v123, v123, v67
	v_add_f32_e32 v122, v122, v68
	v_add_f32_e32 v123, v123, v69
	v_cvt_pk_bf16_f32 v234, v62, v63
	s_waitcnt lgkmcnt(14)
	v_mfma_f32_32x32x16_bf16 v[94:109], v[222:225], v[110:113], v[94:109]
	s_waitcnt lgkmcnt(13)
	ds_read_b64_tr_b16 v[222:223], v159 offset:33792
	ds_read_b64_tr_b16 v[224:225], v159 offset:34304
	v_cvt_pk_bf16_f32 v235, v64, v65
	v_cvt_pk_bf16_f32 v236, v66, v67
	v_cvt_pk_bf16_f32 v237, v68, v69
	v_sub_f32_e32 v70, v70, v160
	v_sub_f32_e32 v71, v71, v160
	v_sub_f32_e32 v72, v72, v160
	v_sub_f32_e32 v73, v73, v160
	v_sub_f32_e32 v74, v74, v160
	v_sub_f32_e32 v75, v75, v160
	v_sub_f32_e32 v76, v76, v160
	v_sub_f32_e32 v77, v77, v160
	s_waitcnt lgkmcnt(8)
	s_waitcnt vmcnt(0)
	s_and_saveexec_b64 s[12:13], s[6:7]
	s_cbranch_execz .Lf3_nocwa
	v_xor_b32_e32 v152, 0x80000000, v152
	ds_write_b32 v154, v152 offset:43008
.Lf3_nocwa:
	s_or_b64 exec, exec, s[12:13]
	v_exp_f32_e32 v70, v70
	v_exp_f32_e32 v71, v71
	v_exp_f32_e32 v72, v72
	v_exp_f32_e32 v73, v73
	v_exp_f32_e32 v74, v74
	v_exp_f32_e32 v75, v75
	v_exp_f32_e32 v76, v76
	v_exp_f32_e32 v77, v77
	v_add_f32_e32 v122, v122, v70
	v_add_f32_e32 v123, v123, v71
	v_add_f32_e32 v122, v122, v72
	v_add_f32_e32 v123, v123, v73
	v_add_f32_e32 v122, v122, v74
	v_add_f32_e32 v123, v123, v75
	v_add_f32_e32 v122, v122, v76
	v_add_f32_e32 v123, v123, v77
	v_cvt_pk_bf16_f32 v238, v70, v71
	v_cvt_pk_bf16_f32 v239, v72, v73
	v_cvt_pk_bf16_f32 v240, v74, v75
	v_cvt_pk_bf16_f32 v241, v76, v77
	v_add_f32_e32 v122, v122, v123
	v_add_f32_e32 v161, v161, v122
	s_waitcnt lgkmcnt(0)
	s_barrier
	ds_read_b128 v[46:49], v158 offset:43008
	ds_read_b128 v[50:53], v158 offset:43040
	ds_read_b128 v[54:57], v158 offset:43072
	ds_read_b128 v[58:61], v158 offset:43104
	ds_read_b128 v[62:65], v158 offset:43136
	ds_read_b128 v[66:69], v158 offset:43168
	ds_read_b128 v[70:73], v158 offset:43200
	ds_read_b128 v[74:77], v158 offset:43232
	v_mfma_f32_32x32x16_bf16 v[14:29], v[190:193], v[226:229], v[14:29]
	ds_read_b128 v[190:193], v218
	v_max3_f32 v124, v78, v79, v80
	v_max3_f32 v125, v81, v82, v83
	v_max3_f32 v124, v124, v84, v85
	v_mfma_f32_32x32x16_bf16 v[30:45], v[194:197], v[226:229], v[30:45]
	ds_read_b128 v[194:197], v218 offset:4608
	s_mov_b32 m0, s39
	s_nop 0
	global_load_lds_dwordx4 v[242:243], off
	s_add_i32 m0, s38, 0x3400
	s_nop 0
	global_load_lds_dwordx4 v[114:115], off
	s_and_saveexec_b64 s[12:13], s[6:7]
	s_cbranch_execz .Lf3_nocka
	global_load_dword v152, v[250:251], off
.Lf3_nocka:
	s_or_b64 exec, exec, s[12:13]
	s_mov_b32 m0, s54
	s_nop 0
	global_load_lds_dwordx4 v[246:247], off
	v_max3_f32 v125, v125, v86, v87
	v_max3_f32 v124, v124, v88, v89
	v_max3_f32 v125, v125, v90, v91
	v_mfma_f32_32x32x16_bf16 v[14:29], v[198:201], v[230:233], v[14:29]
	ds_read_b128 v[198:201], v218 offset:32
	v_max3_f32 v124, v124, v92, v93
	v_max3_f32 v125, v125, v94, v95
	v_max3_f32 v124, v124, v96, v97
	v_mfma_f32_32x32x16_bf16 v[30:45], v[202:205], v[230:233], v[30:45]
	ds_read_b128 v[202:205], v218 offset:4640
	v_max3_f32 v125, v125, v98, v99
	v_max3_f32 v124, v124, v100, v101
	v_max3_f32 v125, v125, v102, v103
	v_mfma_f32_32x32x16_bf16 v[14:29], v[206:209], v[234:237], v[14:29]
	ds_read_b128 v[206:209], v218 offset:64
	v_max3_f32 v124, v124, v104, v105
	v_max3_f32 v125, v125, v106, v107
	v_mfma_f32_32x32x16_bf16 v[30:45], v[210:213], v[234:237], v[30:45]
	ds_read_b128 v[210:213], v218 offset:4672
	v_max3_f32 v124, v124, v108, v109
	v_max_f32_e32 v124, v124, v125
	v_mfma_f32_32x32x16_bf16 v[14:29], v[214:217], v[238:241], v[14:29]
	ds_read_b128 v[214:217], v218 offset:96
	v_mov_b32_e32 v125, v124
	s_nop 1
	v_mfma_f32_32x32x16_bf16 v[30:45], v[222:225], v[238:241], v[30:45]
	s_waitcnt lgkmcnt(14)
	ds_read_b128 v[222:225], v218 offset:4704
	v_permlane32_swap_b32_e32 v124, v125
	v_max_f32_e32 v126, v124, v125
	v_lshl_add_u64 v[242:243], v[242:243], 0, s[46:47]
	v_lshl_add_u64 v[114:115], v[114:115], 0, s[46:47]
	v_lshl_add_u64 v[246:247], v[246:247], 0, s[46:47]
	v_add_f32_e32 v127, 0x41800000, v160
	v_cmp_gt_f32_e32 vcc, v126, v127
	s_cbranch_vccnz .Lf3_rescb
.Lf3_resc_retb:
	s_waitcnt lgkmcnt(7)
	v_mfma_f32_32x32x16_bf16 v[46:61], v[190:193], v[0:3], v[46:61]
	ds_read_b64_tr_b16 v[190:191], v159 offset:34816
	ds_read_b64_tr_b16 v[192:193], v159 offset:35328
	v_sub_f32_e32 v78, v78, v160
	v_sub_f32_e32 v79, v79, v160
	v_sub_f32_e32 v80, v80, v160
	v_sub_f32_e32 v81, v81, v160
	v_sub_f32_e32 v82, v82, v160
	v_sub_f32_e32 v83, v83, v160
	v_sub_f32_e32 v84, v84, v160
	v_sub_f32_e32 v85, v85, v160
	v_exp_f32_e32 v78, v78
	v_exp_f32_e32 v79, v79
	v_exp_f32_e32 v80, v80
	v_exp_f32_e32 v81, v81
	s_waitcnt lgkmcnt(8)
	v_mfma_f32_32x32x16_bf16 v[62:77], v[194:197], v[0:3], v[62:77]
	ds_read_b64_tr_b16 v[194:195], v159 offset:38912
	ds_read_b64_tr_b16 v[196:197], v159 offset:39424
	v_exp_f32_e32 v82, v82
	v_exp_f32_e32 v83, v83
	v_exp_f32_e32 v84, v84
	v_exp_f32_e32 v85, v85
	v_add_f32_e32 v122, v78, v79
	v_add_f32_e32 v123, v80, v81
	v_add_f32_e32 v122, v122, v82
	v_add_f32_e32 v123, v123, v83
	v_add_f32_e32 v122, v122, v84
	v_add_f32_e32 v123, v123, v85
	v_cvt_pk_bf16_f32 v226, v78, v79
	v_cvt_pk_bf16_f32 v227, v80, v81
	s_waitcnt lgkmcnt(9)
	v_mfma_f32_32x32x16_bf16 v[46:61], v[198:201], v[4:7], v[46:61]
	ds_read_b64_tr_b16 v[198:199], v159 offset:35840
	ds_read_b64_tr_b16 v[200:201], v159 offset:36352
	v_cvt_pk_bf16_f32 v228, v82, v83
	v_cvt_pk_bf16_f32 v229, v84, v85
	v_sub_f32_e32 v86, v86, v160
	v_sub_f32_e32 v87, v87, v160
	v_sub_f32_e32 v88, v88, v160
	v_sub_f32_e32 v89, v89, v160
	v_sub_f32_e32 v90, v90, v160
	v_sub_f32_e32 v91, v91, v160
	v_sub_f32_e32 v92, v92, v160
	v_sub_f32_e32 v93, v93, v160
	v_exp_f32_e32 v86, v86
	s_waitcnt lgkmcnt(10)
	v_mfma_f32_32x32x16_bf16 v[62:77], v[202:205], v[4:7], v[62:77]
	ds_read_b64_tr_b16 v[202:203], v159 offset:39936
	ds_read_b64_tr_b16 v[204:205], v159 offset:40448
	v_exp_f32_e32 v87, v87
	v_exp_f32_e32 v88, v88
	v_exp_f32_e32 v89, v89
	v_exp_f32_e32 v90, v90
	v_exp_f32_e32 v91, v91
	v_exp_f32_e32 v92, v92
	v_exp_f32_e32 v93, v93
	v_add_f32_e32 v122, v122, v86
	v_add_f32_e32 v123, v123, v87
	v_add_f32_e32 v122, v122, v88
	v_add_f32_e32 v123, v123, v89
	s_waitcnt lgkmcnt(11)
	v_mfma_f32_32x32x16_bf16 v[46:61], v[206:209], v[8:11], v[46:61]
	ds_read_b64_tr_b16 v[206:207], v159 offset:36864
	ds_read_b64_tr_b16 v[208:209], v159 offset:37376
	v_add_f32_e32 v122, v122, v90
	v_add_f32_e32 v123, v123, v91
	v_add_f32_e32 v122, v122, v92
	v_add_f32_e32 v123, v123, v93
	v_cvt_pk_bf16_f32 v230, v86, v87
	v_cvt_pk_bf16_f32 v231, v88, v89
	v_cvt_pk_bf16_f32 v232, v90, v91
	v_cvt_pk_bf16_f32 v233, v92, v93
	v_sub_f32_e32 v94, v94, v160
	v_sub_f32_e32 v95, v95, v160
	v_sub_f32_e32 v96, v96, v160
	s_waitcnt lgkmcnt(12)
	v_mfma_f32_32x32x16_bf16 v[62:77], v[210:213], v[8:11], v[62:77]
	ds_read_b64_tr_b16 v[210:211], v159 offset:40960
	ds_read_b64_tr_b16 v[212:213], v159 offset:41472
	v_sub_f32_e32 v97, v97, v160
	v_sub_f32_e32 v98, v98, v160
	v_sub_f32_e32 v99, v99, v160
	v_sub_f32_e32 v100, v100, v160
	v_sub_f32_e32 v101, v101, v160
	v_exp_f32_e32 v94, v94
	v_exp_f32_e32 v95, v95
	v_exp_f32_e32 v96, v96
	v_exp_f32_e32 v97, v97
	v_exp_f32_e32 v98, v98
	v_exp_f32_e32 v99, v99
	s_waitcnt lgkmcnt(13)
	v_mfma_f32_32x32x16_bf16 v[46:61], v[214:217], v[110:113], v[46:61]
	ds_read_b64_tr_b16 v[214:215], v159 offset:37888
	ds_read_b64_tr_b16 v[216:217], v159 offset:38400
	v_exp_f32_e32 v100, v100
	v_exp_f32_e32 v101, v101
	v_add_f32_e32 v122, v122, v94
	v_add_f32_e32 v123, v123, v95
	v_add_f32_e32 v122, v122, v96
	v_add_f32_e32 v123, v123, v97
	v_add_f32_e32 v122, v122, v98
	v_add_f32_e32 v123, v123, v99
	v_add_f32_e32 v122, v122, v100
	v_add_f32_e32 v123, v123, v101
	v_cvt_pk_bf16_f32 v234, v94, v95
	s_waitcnt lgkmcnt(14)
	v_mfma_f32_32x32x16_bf16 v[62:77], v[222:225], v[110:113], v[62:77]
	s_waitcnt lgkmcnt(13)
	ds_read_b64_tr_b16 v[222:223], v159 offset:41984
	ds_read_b64_tr_b16 v[224:225], v159 offset:42496
	v_cvt_pk_bf16_f32 v235, v96, v97
	v_cvt_pk_bf16_f32 v236, v98, v99
	v_cvt_pk_bf16_f32 v237, v100, v101
	v_sub_f32_e32 v102, v102, v160
	v_sub_f32_e32 v103, v103, v160
	v_sub_f32_e32 v104, v104, v160
	v_sub_f32_e32 v105, v105, v160
	v_sub_f32_e32 v106, v106, v160
	v_sub_f32_e32 v107, v107, v160
	v_sub_f32_e32 v108, v108, v160
	v_sub_f32_e32 v109, v109, v160
	s_waitcnt lgkmcnt(8)
	s_waitcnt vmcnt(0)
	s_and_saveexec_b64 s[12:13], s[6:7]
	s_cbranch_execz .Lf3_nocwb
	v_xor_b32_e32 v152, 0x80000000, v152
	ds_write_b32 v154, v152 offset:43264
.Lf3_nocwb:
	s_or_b64 exec, exec, s[12:13]
	v_exp_f32_e32 v102, v102
	v_exp_f32_e32 v103, v103
	v_exp_f32_e32 v104, v104
	v_exp_f32_e32 v105, v105
	v_exp_f32_e32 v106, v106
	v_exp_f32_e32 v107, v107
	v_exp_f32_e32 v108, v108
	v_exp_f32_e32 v109, v109
	v_add_f32_e32 v122, v122, v102
	v_add_f32_e32 v123, v123, v103
	v_add_f32_e32 v122, v122, v104
	v_add_f32_e32 v123, v123, v105
	v_add_f32_e32 v122, v122, v106
	v_add_f32_e32 v123, v123, v107
	v_add_f32_e32 v122, v122, v108
	v_add_f32_e32 v123, v123, v109
	v_cvt_pk_bf16_f32 v238, v102, v103
	v_cvt_pk_bf16_f32 v239, v104, v105
	v_cvt_pk_bf16_f32 v240, v106, v107
	v_cvt_pk_bf16_f32 v241, v108, v109
	v_add_f32_e32 v122, v122, v123
	v_add_f32_e32 v161, v161, v122
	s_waitcnt lgkmcnt(0)
	s_barrier
	ds_read_b128 v[78:81], v158 offset:43264
	ds_read_b128 v[82:85], v158 offset:43296
	ds_read_b128 v[86:89], v158 offset:43328
	ds_read_b128 v[90:93], v158 offset:43360
	ds_read_b128 v[94:97], v158 offset:43392
	ds_read_b128 v[98:101], v158 offset:43424
	ds_read_b128 v[102:105], v158 offset:43456
	ds_read_b128 v[106:109], v158 offset:43488
	v_mfma_f32_32x32x16_bf16 v[14:29], v[190:193], v[226:229], v[14:29]
	ds_read_b128 v[190:193], v218 offset:13312
	v_max3_f32 v124, v46, v47, v48
	v_max3_f32 v125, v49, v50, v51
	v_max3_f32 v124, v124, v52, v53
	v_mfma_f32_32x32x16_bf16 v[30:45], v[194:197], v[226:229], v[30:45]
	ds_read_b128 v[194:197], v218 offset:17920
	s_mov_b32 m0, s34
	s_nop 0
	global_load_lds_dwordx4 v[244:245], off
	s_mov_b32 m0, s38
	s_nop 0
	global_load_lds_dwordx4 v[116:117], off
	s_and_saveexec_b64 s[12:13], s[6:7]
	s_cbranch_execz .Lf3_nockb
	global_load_dword v152, v[250:251], off offset:256
.Lf3_nockb:
	s_or_b64 exec, exec, s[12:13]
	s_mov_b32 m0, s55
	s_nop 0
	global_load_lds_dwordx4 v[248:249], off
	v_max3_f32 v125, v125, v54, v55
	v_max3_f32 v124, v124, v56, v57
	v_max3_f32 v125, v125, v58, v59
	v_mfma_f32_32x32x16_bf16 v[14:29], v[198:201], v[230:233], v[14:29]
	ds_read_b128 v[198:201], v218 offset:13344
	v_max3_f32 v124, v124, v60, v61
	v_max3_f32 v125, v125, v62, v63
	v_max3_f32 v124, v124, v64, v65
	v_mfma_f32_32x32x16_bf16 v[30:45], v[202:205], v[230:233], v[30:45]
	ds_read_b128 v[202:205], v218 offset:17952
	v_max3_f32 v125, v125, v66, v67
	v_max3_f32 v124, v124, v68, v69
	v_max3_f32 v125, v125, v70, v71
	v_mfma_f32_32x32x16_bf16 v[14:29], v[206:209], v[234:237], v[14:29]
	ds_read_b128 v[206:209], v218 offset:13376
	v_max3_f32 v124, v124, v72, v73
	v_max3_f32 v125, v125, v74, v75
	v_mfma_f32_32x32x16_bf16 v[30:45], v[210:213], v[234:237], v[30:45]
	ds_read_b128 v[210:213], v218 offset:17984
	v_max3_f32 v124, v124, v76, v77
	v_max_f32_e32 v124, v124, v125
	v_mfma_f32_32x32x16_bf16 v[14:29], v[214:217], v[238:241], v[14:29]
	ds_read_b128 v[214:217], v218 offset:13408
	v_mov_b32_e32 v125, v124
	s_nop 1
	v_mfma_f32_32x32x16_bf16 v[30:45], v[222:225], v[238:241], v[30:45]
	s_waitcnt lgkmcnt(14)
	ds_read_b128 v[222:225], v218 offset:18016
	v_permlane32_swap_b32_e32 v124, v125
	v_max_f32_e32 v126, v124, v125
	v_lshl_add_u64 v[244:245], v[244:245], 0, s[46:47]
	v_lshl_add_u64 v[116:117], v[116:117], 0, s[46:47]
	v_lshl_add_u64 v[248:249], v[248:249], 0, s[46:47]
	v_lshl_add_u64 v[250:251], v[250:251], 0, s[48:49]
	s_add_i32 s10, s10, 2
	s_add_i32 s12, s10, 6
	s_cmp_lt_i32 s12, s41
	s_cbranch_scc1 .Lf3_loop

.Lf3_nockt0FULL:
	s_or_b64 exec, exec, s[12:13]
	s_mov_b32 m0, s54
	s_nop 0
	global_load_lds_dwordx4 v[246:247], off
	v_max3_f32 v125, v125, v86, v87
	v_max3_f32 v124, v124, v88, v89
	v_max3_f32 v125, v125, v90, v91
	v_mfma_f32_32x32x16_bf16 v[14:29], v[198:201], v[230:233], v[14:29]
	ds_read_b128 v[198:201], v218 offset:32
	v_max3_f32 v124, v124, v92, v93
	v_max3_f32 v125, v125, v94, v95
	v_max3_f32 v124, v124, v96, v97
	v_mfma_f32_32x32x16_bf16 v[30:45], v[202:205], v[230:233], v[30:45]
	ds_read_b128 v[202:205], v218 offset:4640
	v_max3_f32 v125, v125, v98, v99
	v_max3_f32 v124, v124, v100, v101
	v_max3_f32 v125, v125, v102, v103
	v_mfma_f32_32x32x16_bf16 v[14:29], v[206:209], v[234:237], v[14:29]
	ds_read_b128 v[206:209], v218 offset:64
	v_max3_f32 v124, v124, v104, v105
	v_max3_f32 v125, v125, v106, v107
	v_mfma_f32_32x32x16_bf16 v[30:45], v[210:213], v[234:237], v[30:45]
	ds_read_b128 v[210:213], v218 offset:4672
	v_max3_f32 v124, v124, v108, v109
	v_max_f32_e32 v124, v124, v125
	v_mfma_f32_32x32x16_bf16 v[14:29], v[214:217], v[238:241], v[14:29]
	ds_read_b128 v[214:217], v218 offset:96
	v_mov_b32_e32 v125, v124
	s_nop 1
	v_mfma_f32_32x32x16_bf16 v[30:45], v[222:225], v[238:241], v[30:45]
	s_waitcnt lgkmcnt(14)
	ds_read_b128 v[222:225], v218 offset:4704
	v_permlane32_swap_b32_e32 v124, v125
	v_max_f32_e32 v126, v124, v125
	v_lshl_add_u64 v[242:243], v[242:243], 0, s[46:47]
	v_lshl_add_u64 v[114:115], v[114:115], 0, s[46:47]
	v_lshl_add_u64 v[246:247], v[246:247], 0, s[46:47]

.Lf3_nocwt1FULLM:
	s_or_b64 exec, exec, s[12:13]
	v_exp_f32_e32 v102, v102
	v_exp_f32_e32 v103, v103
	v_exp_f32_e32 v104, v104
	v_exp_f32_e32 v105, v105
	v_exp_f32_e32 v106, v106
	v_exp_f32_e32 v107, v107
	v_exp_f32_e32 v108, v108
	v_exp_f32_e32 v109, v109
	v_add_f32_e32 v122, v122, v102
	v_add_f32_e32 v123, v123, v103
	v_add_f32_e32 v122, v122, v104
	v_add_f32_e32 v123, v123, v105
	v_add_f32_e32 v122, v122, v106
	v_add_f32_e32 v123, v123, v107
	v_add_f32_e32 v122, v122, v108
	v_add_f32_e32 v123, v123, v109
	v_cvt_pk_bf16_f32 v238, v102, v103
	v_cvt_pk_bf16_f32 v239, v104, v105
	v_cvt_pk_bf16_f32 v240, v106, v107
	v_cvt_pk_bf16_f32 v241, v108, v109
	v_add_f32_e32 v122, v122, v123
	v_add_f32_e32 v161, v161, v122
	s_waitcnt lgkmcnt(0)
	s_barrier
	ds_read_b128 v[78:81], v158 offset:43264
	ds_read_b128 v[82:85], v158 offset:43296
	ds_read_b128 v[86:89], v158 offset:43328
	ds_read_b128 v[90:93], v158 offset:43360
	ds_read_b128 v[94:97], v158 offset:43392
	ds_read_b128 v[98:101], v158 offset:43424
	ds_read_b128 v[102:105], v158 offset:43456
	ds_read_b128 v[106:109], v158 offset:43488
	v_mfma_f32_32x32x16_bf16 v[14:29], v[190:193], v[226:229], v[14:29]
	ds_read_b128 v[190:193], v218 offset:13312
	v_cmp_le_i32_e64 s[52:53], 0, v219
	v_cmp_le_i32_e64 s[14:15], 32, v219
	v_cmp_le_i32_e64 s[16:17], 1, v219
	v_cndmask_b32_e64 v46, v220, v46, s[52:53]
	v_cmp_le_i32_e64 s[52:53], 33, v219
	v_cndmask_b32_e64 v62, v220, v62, s[14:15]
	v_cmp_le_i32_e64 s[14:15], 2, v219
	v_cndmask_b32_e64 v47, v220, v47, s[16:17]
	v_cmp_le_i32_e64 s[16:17], 34, v219
	v_cndmask_b32_e64 v63, v220, v63, s[52:53]
	v_cmp_le_i32_e64 s[52:53], 3, v219
	v_mfma_f32_32x32x16_bf16 v[30:45], v[194:197], v[226:229], v[30:45]
	ds_read_b128 v[194:197], v218 offset:17920
	s_mov_b32 m0, s34
	s_nop 0
	global_load_lds_dwordx4 v[244:245], off
	s_mov_b32 m0, s38
	s_nop 0
	global_load_lds_dwordx4 v[116:117], off
	s_and_saveexec_b64 s[12:13], s[6:7]
	s_cbranch_execz .Lf3_nockt1FULLM
	global_load_dword v152, v[250:251], off offset:256
.Lf3_nockt1FULLM:
	s_or_b64 exec, exec, s[12:13]
	s_mov_b32 m0, s55
	s_nop 0
	global_load_lds_dwordx4 v[248:249], off
	v_cndmask_b32_e64 v48, v220, v48, s[14:15]
	v_cmp_le_i32_e64 s[14:15], 35, v219
	v_cndmask_b32_e64 v64, v220, v64, s[16:17]
	v_cmp_le_i32_e64 s[16:17], 8, v219
	v_cndmask_b32_e64 v49, v220, v49, s[52:53]
	v_cmp_le_i32_e64 s[52:53], 40, v219
	v_cndmask_b32_e64 v65, v220, v65, s[14:15]
	v_cmp_le_i32_e64 s[14:15], 9, v219
	v_cndmask_b32_e64 v50, v220, v50, s[16:17]
	v_cmp_le_i32_e64 s[16:17], 41, v219
	v_cndmask_b32_e64 v66, v220, v66, s[52:53]
	v_mfma_f32_32x32x16_bf16 v[14:29], v[198:201], v[230:233], v[14:29]
	ds_read_b128 v[198:201], v218 offset:13344
	v_cmp_le_i32_e64 s[52:53], 10, v219
	v_cndmask_b32_e64 v51, v220, v51, s[14:15]
	v_cmp_le_i32_e64 s[14:15], 42, v219
	v_cndmask_b32_e64 v67, v220, v67, s[16:17]
	v_cmp_le_i32_e64 s[16:17], 11, v219
	v_cndmask_b32_e64 v52, v220, v52, s[52:53]
	v_cmp_le_i32_e64 s[52:53], 43, v219
	v_cndmask_b32_e64 v68, v220, v68, s[14:15]
	v_cmp_le_i32_e64 s[14:15], 16, v219
	v_cndmask_b32_e64 v53, v220, v53, s[16:17]
	v_cmp_le_i32_e64 s[16:17], 48, v219
	v_mfma_f32_32x32x16_bf16 v[30:45], v[202:205], v[230:233], v[30:45]
	ds_read_b128 v[202:205], v218 offset:17952
	v_cndmask_b32_e64 v69, v220, v69, s[52:53]
	v_cmp_le_i32_e64 s[52:53], 17, v219
	v_cndmask_b32_e64 v54, v220, v54, s[14:15]
	v_cmp_le_i32_e64 s[14:15], 49, v219
	v_cndmask_b32_e64 v70, v220, v70, s[16:17]
	v_cmp_le_i32_e64 s[16:17], 18, v219
	v_cndmask_b32_e64 v55, v220, v55, s[52:53]
	v_cmp_le_i32_e64 s[52:53], 50, v219
	v_cndmask_b32_e64 v71, v220, v71, s[14:15]
	v_cmp_le_i32_e64 s[14:15], 19, v219
	v_cndmask_b32_e64 v56, v220, v56, s[16:17]
	v_mfma_f32_32x32x16_bf16 v[14:29], v[206:209], v[234:237], v[14:29]
	ds_read_b128 v[206:209], v218 offset:13376
	v_cmp_le_i32_e64 s[16:17], 51, v219
	v_cndmask_b32_e64 v72, v220, v72, s[52:53]
	v_cmp_le_i32_e64 s[52:53], 24, v219
	v_cndmask_b32_e64 v57, v220, v57, s[14:15]
	v_cmp_le_i32_e64 s[14:15], 56, v219
	v_cndmask_b32_e64 v73, v220, v73, s[16:17]
	v_cmp_le_i32_e64 s[16:17], 25, v219
	v_cndmask_b32_e64 v58, v220, v58, s[52:53]
	v_cmp_le_i32_e64 s[52:53], 57, v219
	v_cndmask_b32_e64 v74, v220, v74, s[14:15]
	v_mfma_f32_32x32x16_bf16 v[30:45], v[210:213], v[234:237], v[30:45]
	ds_read_b128 v[210:213], v218 offset:17984
	v_cmp_le_i32_e64 s[14:15], 26, v219
	v_cndmask_b32_e64 v59, v220, v59, s[16:17]
	v_cmp_le_i32_e64 s[16:17], 58, v219
	v_cndmask_b32_e64 v75, v220, v75, s[52:53]
	v_cmp_le_i32_e64 s[52:53], 27, v219
	v_cndmask_b32_e64 v60, v220, v60, s[14:15]
	v_cmp_le_i32_e64 s[14:15], 59, v219
	v_cndmask_b32_e64 v76, v220, v76, s[16:17]
	v_cndmask_b32_e64 v61, v220, v61, s[52:53]
	v_cndmask_b32_e64 v77, v220, v77, s[14:15]
	v_mfma_f32_32x32x16_bf16 v[14:29], v[214:217], v[238:241], v[14:29]
	ds_read_b128 v[214:217], v218 offset:13408
	v_max3_f32 v124, v46, v47, v48
	v_max3_f32 v125, v49, v50, v51
	v_max3_f32 v124, v124, v52, v53
	v_max3_f32 v125, v125, v54, v55
	v_max3_f32 v124, v124, v56, v57
	v_max3_f32 v125, v125, v58, v59
	v_max3_f32 v124, v124, v60, v61
	v_max3_f32 v125, v125, v62, v63
	v_max3_f32 v124, v124, v64, v65
	v_max3_f32 v125, v125, v66, v67
	v_mfma_f32_32x32x16_bf16 v[30:45], v[222:225], v[238:241], v[30:45]
	s_waitcnt lgkmcnt(14)
	ds_read_b128 v[222:225], v218 offset:18016
	v_max3_f32 v124, v124, v68, v69
	v_max3_f32 v125, v125, v70, v71
	v_max3_f32 v124, v124, v72, v73
	v_max3_f32 v125, v125, v74, v75
	v_max3_f32 v124, v124, v76, v77
	v_max_f32_e32 v124, v124, v125
	v_mov_b32_e32 v125, v124
	s_nop 1
	v_permlane32_swap_b32_e32 v124, v125
	v_max_f32_e32 v126, v124, v125
	v_lshl_add_u64 v[244:245], v[244:245], 0, s[46:47]
	v_lshl_add_u64 v[116:117], v[116:117], 0, s[46:47]
	v_lshl_add_u64 v[248:249], v[248:249], 0, s[46:47]
	v_lshl_add_u64 v[250:251], v[250:251], 0, s[48:49]
	s_branch .Lf3_tail2

.Lf3_nockt1FULL:
	s_or_b64 exec, exec, s[12:13]
	s_mov_b32 m0, s55
	s_nop 0
	global_load_lds_dwordx4 v[248:249], off
	v_max3_f32 v125, v125, v54, v55
	v_max3_f32 v124, v124, v56, v57
	v_max3_f32 v125, v125, v58, v59
	v_mfma_f32_32x32x16_bf16 v[14:29], v[198:201], v[230:233], v[14:29]
	ds_read_b128 v[198:201], v218 offset:13344
	v_max3_f32 v124, v124, v60, v61
	v_max3_f32 v125, v125, v62, v63
	v_max3_f32 v124, v124, v64, v65
	v_mfma_f32_32x32x16_bf16 v[30:45], v[202:205], v[230:233], v[30:45]
	ds_read_b128 v[202:205], v218 offset:17952
	v_max3_f32 v125, v125, v66, v67
	v_max3_f32 v124, v124, v68, v69
	v_max3_f32 v125, v125, v70, v71
	v_mfma_f32_32x32x16_bf16 v[14:29], v[206:209], v[234:237], v[14:29]
	ds_read_b128 v[206:209], v218 offset:13376
	v_max3_f32 v124, v124, v72, v73
	v_max3_f32 v125, v125, v74, v75
	v_mfma_f32_32x32x16_bf16 v[30:45], v[210:213], v[234:237], v[30:45]
	ds_read_b128 v[210:213], v218 offset:17984
	v_max3_f32 v124, v124, v76, v77
	v_max_f32_e32 v124, v124, v125
	v_mfma_f32_32x32x16_bf16 v[14:29], v[214:217], v[238:241], v[14:29]
	ds_read_b128 v[214:217], v218 offset:13408
	v_mov_b32_e32 v125, v124
	s_nop 1
	v_mfma_f32_32x32x16_bf16 v[30:45], v[222:225], v[238:241], v[30:45]
	s_waitcnt lgkmcnt(14)
	ds_read_b128 v[222:225], v218 offset:18016
	v_permlane32_swap_b32_e32 v124, v125
	v_max_f32_e32 v126, v124, v125
	v_lshl_add_u64 v[244:245], v[244:245], 0, s[46:47]
	v_lshl_add_u64 v[116:117], v[116:117], 0, s[46:47]
	v_lshl_add_u64 v[248:249], v[248:249], 0, s[46:47]
	v_lshl_add_u64 v[250:251], v[250:251], 0, s[48:49]

.Lf3_resc_rett2CONLY:
	s_waitcnt lgkmcnt(0)
	ds_read_b64_tr_b16 v[190:191], v159 offset:26624
	ds_read_b64_tr_b16 v[192:193], v159 offset:27136
	ds_read_b64_tr_b16 v[194:195], v159 offset:30720
	ds_read_b64_tr_b16 v[196:197], v159 offset:31232
	ds_read_b64_tr_b16 v[198:199], v159 offset:27648
	ds_read_b64_tr_b16 v[200:201], v159 offset:28160
	ds_read_b64_tr_b16 v[202:203], v159 offset:31744
	ds_read_b64_tr_b16 v[204:205], v159 offset:32256
	ds_read_b64_tr_b16 v[206:207], v159 offset:28672
	ds_read_b64_tr_b16 v[208:209], v159 offset:29184
	ds_read_b64_tr_b16 v[210:211], v159 offset:32768
	ds_read_b64_tr_b16 v[212:213], v159 offset:33280
	ds_read_b64_tr_b16 v[214:215], v159 offset:29696
	ds_read_b64_tr_b16 v[216:217], v159 offset:30208
	v_sub_f32_e32 v46, v46, v160
	v_sub_f32_e32 v47, v47, v160
	v_sub_f32_e32 v48, v48, v160
	v_sub_f32_e32 v49, v49, v160
	v_sub_f32_e32 v50, v50, v160
	v_sub_f32_e32 v51, v51, v160
	v_sub_f32_e32 v52, v52, v160
	v_sub_f32_e32 v53, v53, v160
	v_exp_f32_e32 v46, v46
	v_exp_f32_e32 v47, v47
	v_exp_f32_e32 v48, v48
	v_exp_f32_e32 v49, v49
	v_exp_f32_e32 v50, v50
	v_exp_f32_e32 v51, v51
	v_exp_f32_e32 v52, v52
	v_exp_f32_e32 v53, v53
	v_add_f32_e32 v122, v46, v47
	v_add_f32_e32 v123, v48, v49
	v_add_f32_e32 v122, v122, v50
	v_add_f32_e32 v123, v123, v51
	v_add_f32_e32 v122, v122, v52
	v_add_f32_e32 v123, v123, v53
	v_cvt_pk_bf16_f32 v226, v46, v47
	v_cvt_pk_bf16_f32 v227, v48, v49
	v_cvt_pk_bf16_f32 v228, v50, v51
	v_cvt_pk_bf16_f32 v229, v52, v53
	v_sub_f32_e32 v54, v54, v160
	v_sub_f32_e32 v55, v55, v160
	v_sub_f32_e32 v56, v56, v160
	v_sub_f32_e32 v57, v57, v160
	v_sub_f32_e32 v58, v58, v160
	v_sub_f32_e32 v59, v59, v160
	v_sub_f32_e32 v60, v60, v160
	v_sub_f32_e32 v61, v61, v160
	v_exp_f32_e32 v54, v54
	v_exp_f32_e32 v55, v55
	v_exp_f32_e32 v56, v56
	v_exp_f32_e32 v57, v57
	v_exp_f32_e32 v58, v58
	v_exp_f32_e32 v59, v59
	v_exp_f32_e32 v60, v60
	v_exp_f32_e32 v61, v61
	v_add_f32_e32 v122, v122, v54
	v_add_f32_e32 v123, v123, v55
	v_add_f32_e32 v122, v122, v56
	v_add_f32_e32 v123, v123, v57
	v_add_f32_e32 v122, v122, v58
	v_add_f32_e32 v123, v123, v59
	v_add_f32_e32 v122, v122, v60
	v_add_f32_e32 v123, v123, v61
	v_cvt_pk_bf16_f32 v230, v54, v55
	v_cvt_pk_bf16_f32 v231, v56, v57
	v_cvt_pk_bf16_f32 v232, v58, v59
	v_cvt_pk_bf16_f32 v233, v60, v61
	v_sub_f32_e32 v62, v62, v160
	v_sub_f32_e32 v63, v63, v160
	v_sub_f32_e32 v64, v64, v160
	v_sub_f32_e32 v65, v65, v160
	v_sub_f32_e32 v66, v66, v160
	v_sub_f32_e32 v67, v67, v160
	v_sub_f32_e32 v68, v68, v160
	v_sub_f32_e32 v69, v69, v160
	v_exp_f32_e32 v62, v62
	v_exp_f32_e32 v63, v63
	v_exp_f32_e32 v64, v64
	v_exp_f32_e32 v65, v65
	v_exp_f32_e32 v66, v66
	v_exp_f32_e32 v67, v67
	v_exp_f32_e32 v68, v68
	v_exp_f32_e32 v69, v69
	v_add_f32_e32 v122, v122, v62
	v_add_f32_e32 v123, v123, v63
	v_add_f32_e32 v122, v122, v64
	v_add_f32_e32 v123, v123, v65
	v_add_f32_e32 v122, v122, v66
	v_add_f32_e32 v123, v123, v67
	v_add_f32_e32 v122, v122, v68
	v_add_f32_e32 v123, v123, v69
	v_cvt_pk_bf16_f32 v234, v62, v63
	v_cvt_pk_bf16_f32 v235, v64, v65
	v_cvt_pk_bf16_f32 v236, v66, v67
	v_cvt_pk_bf16_f32 v237, v68, v69
	v_sub_f32_e32 v70, v70, v160
	v_sub_f32_e32 v71, v71, v160
	v_sub_f32_e32 v72, v72, v160
	v_sub_f32_e32 v73, v73, v160
	v_sub_f32_e32 v74, v74, v160
	v_sub_f32_e32 v75, v75, v160
	v_sub_f32_e32 v76, v76, v160
	v_sub_f32_e32 v77, v77, v160
	v_exp_f32_e32 v70, v70
	v_exp_f32_e32 v71, v71
	v_exp_f32_e32 v72, v72
	v_exp_f32_e32 v73, v73
	v_exp_f32_e32 v74, v74
	v_exp_f32_e32 v75, v75
	v_exp_f32_e32 v76, v76
	v_exp_f32_e32 v77, v77
	v_add_f32_e32 v122, v122, v70
	v_add_f32_e32 v123, v123, v71
	v_add_f32_e32 v122, v122, v72
	v_add_f32_e32 v123, v123, v73
	v_add_f32_e32 v122, v122, v74
	v_add_f32_e32 v123, v123, v75
	v_add_f32_e32 v122, v122, v76
	v_add_f32_e32 v123, v123, v77
	v_cvt_pk_bf16_f32 v238, v70, v71
	v_cvt_pk_bf16_f32 v239, v72, v73
	v_cvt_pk_bf16_f32 v240, v74, v75
	v_cvt_pk_bf16_f32 v241, v76, v77
	v_add_f32_e32 v122, v122, v123
	v_add_f32_e32 v161, v161, v122
	s_waitcnt lgkmcnt(8)
	ds_read_b64_tr_b16 v[222:223], v159 offset:33792
	ds_read_b64_tr_b16 v[224:225], v159 offset:34304
	s_waitcnt vmcnt(0)
	s_and_saveexec_b64 s[12:13], s[6:7]
	s_cbranch_execz .Lf3_nocwt2CONLY
	v_xor_b32_e32 v152, 0x80000000, v152
	ds_write_b32 v154, v152 offset:43008
.Lf3_nocwt2CONLY:
	s_or_b64 exec, exec, s[12:13]
	s_waitcnt lgkmcnt(0)
	s_barrier
	v_mfma_f32_32x32x16_bf16 v[14:29], v[190:193], v[226:229], v[14:29]
	v_mfma_f32_32x32x16_bf16 v[30:45], v[194:197], v[226:229], v[30:45]
	s_mov_b32 m0, s39
	s_nop 0
	global_load_lds_dwordx4 v[242:243], off
	s_add_i32 m0, s38, 0x3400
	s_nop 0
	global_load_lds_dwordx4 v[114:115], off
	s_and_saveexec_b64 s[12:13], s[6:7]
	s_cbranch_execz .Lf3_nockt2CONLY
	global_load_dword v152, v[250:251], off
.Lf3_nockt2CONLY:
	s_or_b64 exec, exec, s[12:13]
	s_mov_b32 m0, s54
	s_nop 0
	global_load_lds_dwordx4 v[246:247], off
	v_mfma_f32_32x32x16_bf16 v[14:29], v[198:201], v[230:233], v[14:29]
	v_mfma_f32_32x32x16_bf16 v[30:45], v[202:205], v[230:233], v[30:45]
	v_mfma_f32_32x32x16_bf16 v[14:29], v[206:209], v[234:237], v[14:29]
	v_mfma_f32_32x32x16_bf16 v[30:45], v[210:213], v[234:237], v[30:45]
	v_mfma_f32_32x32x16_bf16 v[14:29], v[214:217], v[238:241], v[14:29]
	v_mfma_f32_32x32x16_bf16 v[30:45], v[222:225], v[238:241], v[30:45]
	v_lshl_add_u64 v[242:243], v[242:243], 0, s[46:47]
	v_lshl_add_u64 v[114:115], v[114:115], 0, s[46:47]
	v_lshl_add_u64 v[246:247], v[246:247], 0, s[46:47]
	s_branch .Lf3_tail3

.Lf3_nockt2FULL:
	s_or_b64 exec, exec, s[12:13]
	s_mov_b32 m0, s54
	s_nop 0
	global_load_lds_dwordx4 v[246:247], off
	v_max3_f32 v125, v125, v86, v87
	v_max3_f32 v124, v124, v88, v89
	v_max3_f32 v125, v125, v90, v91
	v_mfma_f32_32x32x16_bf16 v[14:29], v[198:201], v[230:233], v[14:29]
	ds_read_b128 v[198:201], v218 offset:32
	v_max3_f32 v124, v124, v92, v93
	v_max3_f32 v125, v125, v94, v95
	v_max3_f32 v124, v124, v96, v97
	v_mfma_f32_32x32x16_bf16 v[30:45], v[202:205], v[230:233], v[30:45]
	ds_read_b128 v[202:205], v218 offset:4640
	v_max3_f32 v125, v125, v98, v99
	v_max3_f32 v124, v124, v100, v101
	v_max3_f32 v125, v125, v102, v103
	v_mfma_f32_32x32x16_bf16 v[14:29], v[206:209], v[234:237], v[14:29]
	ds_read_b128 v[206:209], v218 offset:64
	v_max3_f32 v124, v124, v104, v105
	v_max3_f32 v125, v125, v106, v107
	v_mfma_f32_32x32x16_bf16 v[30:45], v[210:213], v[234:237], v[30:45]
	ds_read_b128 v[210:213], v218 offset:4672
	v_max3_f32 v124, v124, v108, v109
	v_max_f32_e32 v124, v124, v125
	v_mfma_f32_32x32x16_bf16 v[14:29], v[214:217], v[238:241], v[14:29]
	ds_read_b128 v[214:217], v218 offset:96
	v_mov_b32_e32 v125, v124
	s_nop 1
	v_mfma_f32_32x32x16_bf16 v[30:45], v[222:225], v[238:241], v[30:45]
	s_waitcnt lgkmcnt(14)
	ds_read_b128 v[222:225], v218 offset:4704
	v_permlane32_swap_b32_e32 v124, v125
	v_max_f32_e32 v126, v124, v125
	v_lshl_add_u64 v[242:243], v[242:243], 0, s[46:47]
	v_lshl_add_u64 v[114:115], v[114:115], 0, s[46:47]
	v_lshl_add_u64 v[246:247], v[246:247], 0, s[46:47]
	s_branch .Lf3_tail3

.Lf3_nocwt2FULLM:
	s_or_b64 exec, exec, s[12:13]
	v_exp_f32_e32 v70, v70
	v_exp_f32_e32 v71, v71
	v_exp_f32_e32 v72, v72
	v_exp_f32_e32 v73, v73
	v_exp_f32_e32 v74, v74
	v_exp_f32_e32 v75, v75
	v_exp_f32_e32 v76, v76
	v_exp_f32_e32 v77, v77
	v_add_f32_e32 v122, v122, v70
	v_add_f32_e32 v123, v123, v71
	v_add_f32_e32 v122, v122, v72
	v_add_f32_e32 v123, v123, v73
	v_add_f32_e32 v122, v122, v74
	v_add_f32_e32 v123, v123, v75
	v_add_f32_e32 v122, v122, v76
	v_add_f32_e32 v123, v123, v77
	v_cvt_pk_bf16_f32 v238, v70, v71
	v_cvt_pk_bf16_f32 v239, v72, v73
	v_cvt_pk_bf16_f32 v240, v74, v75
	v_cvt_pk_bf16_f32 v241, v76, v77
	v_add_f32_e32 v122, v122, v123
	v_add_f32_e32 v161, v161, v122
	s_waitcnt lgkmcnt(0)
	s_barrier
	ds_read_b128 v[46:49], v158 offset:43008
	ds_read_b128 v[50:53], v158 offset:43040
	ds_read_b128 v[54:57], v158 offset:43072
	ds_read_b128 v[58:61], v158 offset:43104
	ds_read_b128 v[62:65], v158 offset:43136
	ds_read_b128 v[66:69], v158 offset:43168
	ds_read_b128 v[70:73], v158 offset:43200
	ds_read_b128 v[74:77], v158 offset:43232
	v_mfma_f32_32x32x16_bf16 v[14:29], v[190:193], v[226:229], v[14:29]
	ds_read_b128 v[190:193], v218
	v_cmp_le_i32_e64 s[52:53], 0, v219
	v_cmp_le_i32_e64 s[14:15], 32, v219
	v_cmp_le_i32_e64 s[16:17], 1, v219
	v_cndmask_b32_e64 v78, v220, v78, s[52:53]
	v_cmp_le_i32_e64 s[52:53], 33, v219
	v_cndmask_b32_e64 v94, v220, v94, s[14:15]
	v_cmp_le_i32_e64 s[14:15], 2, v219
	v_cndmask_b32_e64 v79, v220, v79, s[16:17]
	v_cmp_le_i32_e64 s[16:17], 34, v219
	v_cndmask_b32_e64 v95, v220, v95, s[52:53]
	v_cmp_le_i32_e64 s[52:53], 3, v219
	v_mfma_f32_32x32x16_bf16 v[30:45], v[194:197], v[226:229], v[30:45]
	ds_read_b128 v[194:197], v218 offset:4608
	s_mov_b32 m0, s39
	s_nop 0
	global_load_lds_dwordx4 v[242:243], off
	s_add_i32 m0, s38, 0x3400
	s_nop 0
	global_load_lds_dwordx4 v[114:115], off
	s_and_saveexec_b64 s[12:13], s[6:7]
	s_cbranch_execz .Lf3_nockt2FULLM
	global_load_dword v152, v[250:251], off
.Lf3_nockt2FULLM:
	s_or_b64 exec, exec, s[12:13]
	s_mov_b32 m0, s54
	s_nop 0
	global_load_lds_dwordx4 v[246:247], off
	v_cndmask_b32_e64 v80, v220, v80, s[14:15]
	v_cmp_le_i32_e64 s[14:15], 35, v219
	v_cndmask_b32_e64 v96, v220, v96, s[16:17]
	v_cmp_le_i32_e64 s[16:17], 8, v219
	v_cndmask_b32_e64 v81, v220, v81, s[52:53]
	v_cmp_le_i32_e64 s[52:53], 40, v219
	v_cndmask_b32_e64 v97, v220, v97, s[14:15]
	v_cmp_le_i32_e64 s[14:15], 9, v219
	v_cndmask_b32_e64 v82, v220, v82, s[16:17]
	v_cmp_le_i32_e64 s[16:17], 41, v219
	v_cndmask_b32_e64 v98, v220, v98, s[52:53]
	v_mfma_f32_32x32x16_bf16 v[14:29], v[198:201], v[230:233], v[14:29]
	ds_read_b128 v[198:201], v218 offset:32
	v_cmp_le_i32_e64 s[52:53], 10, v219
	v_cndmask_b32_e64 v83, v220, v83, s[14:15]
	v_cmp_le_i32_e64 s[14:15], 42, v219
	v_cndmask_b32_e64 v99, v220, v99, s[16:17]
	v_cmp_le_i32_e64 s[16:17], 11, v219
	v_cndmask_b32_e64 v84, v220, v84, s[52:53]
	v_cmp_le_i32_e64 s[52:53], 43, v219
	v_cndmask_b32_e64 v100, v220, v100, s[14:15]
	v_cmp_le_i32_e64 s[14:15], 16, v219
	v_cndmask_b32_e64 v85, v220, v85, s[16:17]
	v_cmp_le_i32_e64 s[16:17], 48, v219
	v_mfma_f32_32x32x16_bf16 v[30:45], v[202:205], v[230:233], v[30:45]
	ds_read_b128 v[202:205], v218 offset:4640
	v_cndmask_b32_e64 v101, v220, v101, s[52:53]
	v_cmp_le_i32_e64 s[52:53], 17, v219
	v_cndmask_b32_e64 v86, v220, v86, s[14:15]
	v_cmp_le_i32_e64 s[14:15], 49, v219
	v_cndmask_b32_e64 v102, v220, v102, s[16:17]
	v_cmp_le_i32_e64 s[16:17], 18, v219
	v_cndmask_b32_e64 v87, v220, v87, s[52:53]
	v_cmp_le_i32_e64 s[52:53], 50, v219
	v_cndmask_b32_e64 v103, v220, v103, s[14:15]
	v_cmp_le_i32_e64 s[14:15], 19, v219
	v_cndmask_b32_e64 v88, v220, v88, s[16:17]
	v_mfma_f32_32x32x16_bf16 v[14:29], v[206:209], v[234:237], v[14:29]
	ds_read_b128 v[206:209], v218 offset:64
	v_cmp_le_i32_e64 s[16:17], 51, v219
	v_cndmask_b32_e64 v104, v220, v104, s[52:53]
	v_cmp_le_i32_e64 s[52:53], 24, v219
	v_cndmask_b32_e64 v89, v220, v89, s[14:15]
	v_cmp_le_i32_e64 s[14:15], 56, v219
	v_cndmask_b32_e64 v105, v220, v105, s[16:17]
	v_cmp_le_i32_e64 s[16:17], 25, v219
	v_cndmask_b32_e64 v90, v220, v90, s[52:53]
	v_cmp_le_i32_e64 s[52:53], 57, v219
	v_cndmask_b32_e64 v106, v220, v106, s[14:15]
	v_mfma_f32_32x32x16_bf16 v[30:45], v[210:213], v[234:237], v[30:45]
	ds_read_b128 v[210:213], v218 offset:4672
	v_cmp_le_i32_e64 s[14:15], 26, v219
	v_cndmask_b32_e64 v91, v220, v91, s[16:17]
	v_cmp_le_i32_e64 s[16:17], 58, v219
	v_cndmask_b32_e64 v107, v220, v107, s[52:53]
	v_cmp_le_i32_e64 s[52:53], 27, v219
	v_cndmask_b32_e64 v92, v220, v92, s[14:15]
	v_cmp_le_i32_e64 s[14:15], 59, v219
	v_cndmask_b32_e64 v108, v220, v108, s[16:17]
	v_cndmask_b32_e64 v93, v220, v93, s[52:53]
	v_cndmask_b32_e64 v109, v220, v109, s[14:15]
	v_mfma_f32_32x32x16_bf16 v[14:29], v[214:217], v[238:241], v[14:29]
	ds_read_b128 v[214:217], v218 offset:96
	v_max3_f32 v124, v78, v79, v80
	v_max3_f32 v125, v81, v82, v83
	v_max3_f32 v124, v124, v84, v85
	v_max3_f32 v125, v125, v86, v87
	v_max3_f32 v124, v124, v88, v89
	v_max3_f32 v125, v125, v90, v91
	v_max3_f32 v124, v124, v92, v93
	v_max3_f32 v125, v125, v94, v95
	v_max3_f32 v124, v124, v96, v97
	v_max3_f32 v125, v125, v98, v99
	v_mfma_f32_32x32x16_bf16 v[30:45], v[222:225], v[238:241], v[30:45]
	s_waitcnt lgkmcnt(14)
	ds_read_b128 v[222:225], v218 offset:4704
	v_max3_f32 v124, v124, v100, v101
	v_max3_f32 v125, v125, v102, v103
	v_max3_f32 v124, v124, v104, v105
	v_max3_f32 v125, v125, v106, v107
	v_max3_f32 v124, v124, v108, v109
	v_max_f32_e32 v124, v124, v125
	v_mov_b32_e32 v125, v124
	s_nop 1
	v_permlane32_swap_b32_e32 v124, v125
	v_max_f32_e32 v126, v124, v125
	v_lshl_add_u64 v[242:243], v[242:243], 0, s[46:47]
	v_lshl_add_u64 v[114:115], v[114:115], 0, s[46:47]
	v_lshl_add_u64 v[246:247], v[246:247], 0, s[46:47]
.Lf3_tail3:
	s_cmp_ge_u32 s11, 3
	s_cbranch_scc1 .Lf3_t3_FULL
	s_cmp_eq_u32 s11, 2
	s_cbranch_scc1 .Lf3_t3_FULLM
	s_cmp_eq_u32 s11, 1
	s_cbranch_scc1 .Lf3_t3_CONLY
	s_waitcnt lgkmcnt(0)
	s_waitcnt vmcnt(0)
	s_and_saveexec_b64 s[12:13], s[6:7]
	s_cbranch_execz .Lf3_nocwt3IDLE
	v_xor_b32_e32 v152, 0x80000000, v152
	ds_write_b32 v154, v152 offset:43264
.Lf3_nocwt3IDLE:
	s_or_b64 exec, exec, s[12:13]
	s_waitcnt lgkmcnt(0)
	s_barrier
	s_mov_b32 m0, s55
	s_nop 0
	global_load_lds_dwordx4 v[248:249], off
	v_lshl_add_u64 v[244:245], v[244:245], 0, s[46:47]
	v_lshl_add_u64 v[116:117], v[116:117], 0, s[46:47]
	v_lshl_add_u64 v[248:249], v[248:249], 0, s[46:47]
	v_lshl_add_u64 v[250:251], v[250:251], 0, s[48:49]
	s_branch .Lf3_tail4

.Lf3_nocwt3FULL:
	s_or_b64 exec, exec, s[12:13]
	v_exp_f32_e32 v102, v102
	v_exp_f32_e32 v103, v103
	v_exp_f32_e32 v104, v104
	v_exp_f32_e32 v105, v105
	v_exp_f32_e32 v106, v106
	v_exp_f32_e32 v107, v107
	v_exp_f32_e32 v108, v108
	v_exp_f32_e32 v109, v109
	v_add_f32_e32 v122, v122, v102
	v_add_f32_e32 v123, v123, v103
	v_add_f32_e32 v122, v122, v104
	v_add_f32_e32 v123, v123, v105
	v_add_f32_e32 v122, v122, v106
	v_add_f32_e32 v123, v123, v107
	v_add_f32_e32 v122, v122, v108
	v_add_f32_e32 v123, v123, v109
	v_cvt_pk_bf16_f32 v238, v102, v103
	v_cvt_pk_bf16_f32 v239, v104, v105
	v_cvt_pk_bf16_f32 v240, v106, v107
	v_cvt_pk_bf16_f32 v241, v108, v109
	v_add_f32_e32 v122, v122, v123
	v_add_f32_e32 v161, v161, v122
	s_waitcnt lgkmcnt(0)
	s_barrier
	ds_read_b128 v[78:81], v158 offset:43264
	ds_read_b128 v[82:85], v158 offset:43296
	ds_read_b128 v[86:89], v158 offset:43328
	ds_read_b128 v[90:93], v158 offset:43360
	ds_read_b128 v[94:97], v158 offset:43392
	ds_read_b128 v[98:101], v158 offset:43424
	ds_read_b128 v[102:105], v158 offset:43456
	ds_read_b128 v[106:109], v158 offset:43488
	v_mfma_f32_32x32x16_bf16 v[14:29], v[190:193], v[226:229], v[14:29]
	ds_read_b128 v[190:193], v218 offset:13312
	v_max3_f32 v124, v46, v47, v48
	v_max3_f32 v125, v49, v50, v51
	v_max3_f32 v124, v124, v52, v53
	v_mfma_f32_32x32x16_bf16 v[30:45], v[194:197], v[226:229], v[30:45]
	ds_read_b128 v[194:197], v218 offset:17920
	s_mov_b32 m0, s55
	s_nop 0
	global_load_lds_dwordx4 v[248:249], off
	v_max3_f32 v125, v125, v54, v55
	v_max3_f32 v124, v124, v56, v57
	v_max3_f32 v125, v125, v58, v59
	v_mfma_f32_32x32x16_bf16 v[14:29], v[198:201], v[230:233], v[14:29]
	ds_read_b128 v[198:201], v218 offset:13344
	v_max3_f32 v124, v124, v60, v61
	v_max3_f32 v125, v125, v62, v63
	v_max3_f32 v124, v124, v64, v65
	v_mfma_f32_32x32x16_bf16 v[30:45], v[202:205], v[230:233], v[30:45]
	ds_read_b128 v[202:205], v218 offset:17952
	v_max3_f32 v125, v125, v66, v67
	v_max3_f32 v124, v124, v68, v69
	v_max3_f32 v125, v125, v70, v71
	v_mfma_f32_32x32x16_bf16 v[14:29], v[206:209], v[234:237], v[14:29]
	ds_read_b128 v[206:209], v218 offset:13376
	v_max3_f32 v124, v124, v72, v73
	v_max3_f32 v125, v125, v74, v75
	v_mfma_f32_32x32x16_bf16 v[30:45], v[210:213], v[234:237], v[30:45]
	ds_read_b128 v[210:213], v218 offset:17984
	v_max3_f32 v124, v124, v76, v77
	v_max_f32_e32 v124, v124, v125
	v_mfma_f32_32x32x16_bf16 v[14:29], v[214:217], v[238:241], v[14:29]
	ds_read_b128 v[214:217], v218 offset:13408
	v_mov_b32_e32 v125, v124
	s_nop 1
	v_mfma_f32_32x32x16_bf16 v[30:45], v[222:225], v[238:241], v[30:45]
	s_waitcnt lgkmcnt(14)
	ds_read_b128 v[222:225], v218 offset:18016
	v_permlane32_swap_b32_e32 v124, v125
	v_max_f32_e32 v126, v124, v125
	v_lshl_add_u64 v[244:245], v[244:245], 0, s[46:47]
	v_lshl_add_u64 v[116:117], v[116:117], 0, s[46:47]
	v_lshl_add_u64 v[248:249], v[248:249], 0, s[46:47]
	v_lshl_add_u64 v[250:251], v[250:251], 0, s[48:49]
	s_branch .Lf3_tail4

.Lf3_nocwt3FULLM:
	s_or_b64 exec, exec, s[12:13]
	v_exp_f32_e32 v102, v102
	v_exp_f32_e32 v103, v103
	v_exp_f32_e32 v104, v104
	v_exp_f32_e32 v105, v105
	v_exp_f32_e32 v106, v106
	v_exp_f32_e32 v107, v107
	v_exp_f32_e32 v108, v108
	v_exp_f32_e32 v109, v109
	v_add_f32_e32 v122, v122, v102
	v_add_f32_e32 v123, v123, v103
	v_add_f32_e32 v122, v122, v104
	v_add_f32_e32 v123, v123, v105
	v_add_f32_e32 v122, v122, v106
	v_add_f32_e32 v123, v123, v107
	v_add_f32_e32 v122, v122, v108
	v_add_f32_e32 v123, v123, v109
	v_cvt_pk_bf16_f32 v238, v102, v103
	v_cvt_pk_bf16_f32 v239, v104, v105
	v_cvt_pk_bf16_f32 v240, v106, v107
	v_cvt_pk_bf16_f32 v241, v108, v109
	v_add_f32_e32 v122, v122, v123
	v_add_f32_e32 v161, v161, v122
	s_waitcnt lgkmcnt(0)
	s_barrier
	ds_read_b128 v[78:81], v158 offset:43264
	ds_read_b128 v[82:85], v158 offset:43296
	ds_read_b128 v[86:89], v158 offset:43328
	ds_read_b128 v[90:93], v158 offset:43360
	ds_read_b128 v[94:97], v158 offset:43392
	ds_read_b128 v[98:101], v158 offset:43424
	ds_read_b128 v[102:105], v158 offset:43456
	ds_read_b128 v[106:109], v158 offset:43488
	v_mfma_f32_32x32x16_bf16 v[14:29], v[190:193], v[226:229], v[14:29]
	ds_read_b128 v[190:193], v218 offset:13312
	v_cmp_le_i32_e64 s[52:53], 0, v219
	v_cmp_le_i32_e64 s[14:15], 32, v219
	v_cmp_le_i32_e64 s[16:17], 1, v219
	v_cndmask_b32_e64 v46, v220, v46, s[52:53]
	v_cmp_le_i32_e64 s[52:53], 33, v219
	v_cndmask_b32_e64 v62, v220, v62, s[14:15]
	v_cmp_le_i32_e64 s[14:15], 2, v219
	v_cndmask_b32_e64 v47, v220, v47, s[16:17]
	v_cmp_le_i32_e64 s[16:17], 34, v219
	v_cndmask_b32_e64 v63, v220, v63, s[52:53]
	v_cmp_le_i32_e64 s[52:53], 3, v219
	v_mfma_f32_32x32x16_bf16 v[30:45], v[194:197], v[226:229], v[30:45]
	ds_read_b128 v[194:197], v218 offset:17920
	s_mov_b32 m0, s55
	s_nop 0
	global_load_lds_dwordx4 v[248:249], off
	v_cndmask_b32_e64 v48, v220, v48, s[14:15]
	v_cmp_le_i32_e64 s[14:15], 35, v219
	v_cndmask_b32_e64 v64, v220, v64, s[16:17]
	v_cmp_le_i32_e64 s[16:17], 8, v219
	v_cndmask_b32_e64 v49, v220, v49, s[52:53]
	v_cmp_le_i32_e64 s[52:53], 40, v219
	v_cndmask_b32_e64 v65, v220, v65, s[14:15]
	v_cmp_le_i32_e64 s[14:15], 9, v219
	v_cndmask_b32_e64 v50, v220, v50, s[16:17]
	v_cmp_le_i32_e64 s[16:17], 41, v219
	v_cndmask_b32_e64 v66, v220, v66, s[52:53]
	v_mfma_f32_32x32x16_bf16 v[14:29], v[198:201], v[230:233], v[14:29]
	ds_read_b128 v[198:201], v218 offset:13344
	v_cmp_le_i32_e64 s[52:53], 10, v219
	v_cndmask_b32_e64 v51, v220, v51, s[14:15]
	v_cmp_le_i32_e64 s[14:15], 42, v219
	v_cndmask_b32_e64 v67, v220, v67, s[16:17]
	v_cmp_le_i32_e64 s[16:17], 11, v219
	v_cndmask_b32_e64 v52, v220, v52, s[52:53]
	v_cmp_le_i32_e64 s[52:53], 43, v219
	v_cndmask_b32_e64 v68, v220, v68, s[14:15]
	v_cmp_le_i32_e64 s[14:15], 16, v219
	v_cndmask_b32_e64 v53, v220, v53, s[16:17]
	v_cmp_le_i32_e64 s[16:17], 48, v219
	v_mfma_f32_32x32x16_bf16 v[30:45], v[202:205], v[230:233], v[30:45]
	ds_read_b128 v[202:205], v218 offset:17952
	v_cndmask_b32_e64 v69, v220, v69, s[52:53]
	v_cmp_le_i32_e64 s[52:53], 17, v219
	v_cndmask_b32_e64 v54, v220, v54, s[14:15]
	v_cmp_le_i32_e64 s[14:15], 49, v219
	v_cndmask_b32_e64 v70, v220, v70, s[16:17]
	v_cmp_le_i32_e64 s[16:17], 18, v219
	v_cndmask_b32_e64 v55, v220, v55, s[52:53]
	v_cmp_le_i32_e64 s[52:53], 50, v219
	v_cndmask_b32_e64 v71, v220, v71, s[14:15]
	v_cmp_le_i32_e64 s[14:15], 19, v219
	v_cndmask_b32_e64 v56, v220, v56, s[16:17]
	v_mfma_f32_32x32x16_bf16 v[14:29], v[206:209], v[234:237], v[14:29]
	ds_read_b128 v[206:209], v218 offset:13376
	v_cmp_le_i32_e64 s[16:17], 51, v219
	v_cndmask_b32_e64 v72, v220, v72, s[52:53]
	v_cmp_le_i32_e64 s[52:53], 24, v219
	v_cndmask_b32_e64 v57, v220, v57, s[14:15]
	v_cmp_le_i32_e64 s[14:15], 56, v219
	v_cndmask_b32_e64 v73, v220, v73, s[16:17]
	v_cmp_le_i32_e64 s[16:17], 25, v219
	v_cndmask_b32_e64 v58, v220, v58, s[52:53]
	v_cmp_le_i32_e64 s[52:53], 57, v219
	v_cndmask_b32_e64 v74, v220, v74, s[14:15]
	v_mfma_f32_32x32x16_bf16 v[30:45], v[210:213], v[234:237], v[30:45]
	ds_read_b128 v[210:213], v218 offset:17984
	v_cmp_le_i32_e64 s[14:15], 26, v219
	v_cndmask_b32_e64 v59, v220, v59, s[16:17]
	v_cmp_le_i32_e64 s[16:17], 58, v219
	v_cndmask_b32_e64 v75, v220, v75, s[52:53]
	v_cmp_le_i32_e64 s[52:53], 27, v219
	v_cndmask_b32_e64 v60, v220, v60, s[14:15]
	v_cmp_le_i32_e64 s[14:15], 59, v219
	v_cndmask_b32_e64 v76, v220, v76, s[16:17]
	v_cndmask_b32_e64 v61, v220, v61, s[52:53]
	v_cndmask_b32_e64 v77, v220, v77, s[14:15]
	v_mfma_f32_32x32x16_bf16 v[14:29], v[214:217], v[238:241], v[14:29]
	ds_read_b128 v[214:217], v218 offset:13408
	v_max3_f32 v124, v46, v47, v48
	v_max3_f32 v125, v49, v50, v51
	v_max3_f32 v124, v124, v52, v53
	v_max3_f32 v125, v125, v54, v55
	v_max3_f32 v124, v124, v56, v57
	v_max3_f32 v125, v125, v58, v59
	v_max3_f32 v124, v124, v60, v61
	v_max3_f32 v125, v125, v62, v63
	v_max3_f32 v124, v124, v64, v65
	v_max3_f32 v125, v125, v66, v67
	v_mfma_f32_32x32x16_bf16 v[30:45], v[222:225], v[238:241], v[30:45]
	s_waitcnt lgkmcnt(14)
	ds_read_b128 v[222:225], v218 offset:18016
	v_max3_f32 v124, v124, v68, v69
	v_max3_f32 v125, v125, v70, v71
	v_max3_f32 v124, v124, v72, v73
	v_max3_f32 v125, v125, v74, v75
	v_max3_f32 v124, v124, v76, v77
	v_max_f32_e32 v124, v124, v125
	v_mov_b32_e32 v125, v124
	s_nop 1
	v_permlane32_swap_b32_e32 v124, v125
	v_max_f32_e32 v126, v124, v125
	v_lshl_add_u64 v[244:245], v[244:245], 0, s[46:47]
	v_lshl_add_u64 v[116:117], v[116:117], 0, s[46:47]
	v_lshl_add_u64 v[248:249], v[248:249], 0, s[46:47]
	v_lshl_add_u64 v[250:251], v[250:251], 0, s[48:49]
	s_branch .Lf3_tail4

.Lf3_resc_rett3CONLY:
	s_waitcnt lgkmcnt(0)
	ds_read_b64_tr_b16 v[190:191], v159 offset:34816
	ds_read_b64_tr_b16 v[192:193], v159 offset:35328
	ds_read_b64_tr_b16 v[194:195], v159 offset:38912
	ds_read_b64_tr_b16 v[196:197], v159 offset:39424
	ds_read_b64_tr_b16 v[198:199], v159 offset:35840
	ds_read_b64_tr_b16 v[200:201], v159 offset:36352
	ds_read_b64_tr_b16 v[202:203], v159 offset:39936
	ds_read_b64_tr_b16 v[204:205], v159 offset:40448
	ds_read_b64_tr_b16 v[206:207], v159 offset:36864
	ds_read_b64_tr_b16 v[208:209], v159 offset:37376
	ds_read_b64_tr_b16 v[210:211], v159 offset:40960
	ds_read_b64_tr_b16 v[212:213], v159 offset:41472
	ds_read_b64_tr_b16 v[214:215], v159 offset:37888
	ds_read_b64_tr_b16 v[216:217], v159 offset:38400
	v_sub_f32_e32 v78, v78, v160
	v_sub_f32_e32 v79, v79, v160
	v_sub_f32_e32 v80, v80, v160
	v_sub_f32_e32 v81, v81, v160
	v_sub_f32_e32 v82, v82, v160
	v_sub_f32_e32 v83, v83, v160
	v_sub_f32_e32 v84, v84, v160
	v_sub_f32_e32 v85, v85, v160
	v_exp_f32_e32 v78, v78
	v_exp_f32_e32 v79, v79
	v_exp_f32_e32 v80, v80
	v_exp_f32_e32 v81, v81
	v_exp_f32_e32 v82, v82
	v_exp_f32_e32 v83, v83
	v_exp_f32_e32 v84, v84
	v_exp_f32_e32 v85, v85
	v_add_f32_e32 v122, v78, v79
	v_add_f32_e32 v123, v80, v81
	v_add_f32_e32 v122, v122, v82
	v_add_f32_e32 v123, v123, v83
	v_add_f32_e32 v122, v122, v84
	v_add_f32_e32 v123, v123, v85
	v_cvt_pk_bf16_f32 v226, v78, v79
	v_cvt_pk_bf16_f32 v227, v80, v81
	v_cvt_pk_bf16_f32 v228, v82, v83
	v_cvt_pk_bf16_f32 v229, v84, v85
	v_sub_f32_e32 v86, v86, v160
	v_sub_f32_e32 v87, v87, v160
	v_sub_f32_e32 v88, v88, v160
	v_sub_f32_e32 v89, v89, v160
	v_sub_f32_e32 v90, v90, v160
	v_sub_f32_e32 v91, v91, v160
	v_sub_f32_e32 v92, v92, v160
	v_sub_f32_e32 v93, v93, v160
	v_exp_f32_e32 v86, v86
	v_exp_f32_e32 v87, v87
	v_exp_f32_e32 v88, v88
	v_exp_f32_e32 v89, v89
	v_exp_f32_e32 v90, v90
	v_exp_f32_e32 v91, v91
	v_exp_f32_e32 v92, v92
	v_exp_f32_e32 v93, v93
	v_add_f32_e32 v122, v122, v86
	v_add_f32_e32 v123, v123, v87
	v_add_f32_e32 v122, v122, v88
	v_add_f32_e32 v123, v123, v89
	v_add_f32_e32 v122, v122, v90
	v_add_f32_e32 v123, v123, v91
	v_add_f32_e32 v122, v122, v92
	v_add_f32_e32 v123, v123, v93
	v_cvt_pk_bf16_f32 v230, v86, v87
	v_cvt_pk_bf16_f32 v231, v88, v89
	v_cvt_pk_bf16_f32 v232, v90, v91
	v_cvt_pk_bf16_f32 v233, v92, v93
	v_sub_f32_e32 v94, v94, v160
	v_sub_f32_e32 v95, v95, v160
	v_sub_f32_e32 v96, v96, v160
	v_sub_f32_e32 v97, v97, v160
	v_sub_f32_e32 v98, v98, v160
	v_sub_f32_e32 v99, v99, v160
	v_sub_f32_e32 v100, v100, v160
	v_sub_f32_e32 v101, v101, v160
	v_exp_f32_e32 v94, v94
	v_exp_f32_e32 v95, v95
	v_exp_f32_e32 v96, v96
	v_exp_f32_e32 v97, v97
	v_exp_f32_e32 v98, v98
	v_exp_f32_e32 v99, v99
	v_exp_f32_e32 v100, v100
	v_exp_f32_e32 v101, v101
	v_add_f32_e32 v122, v122, v94
	v_add_f32_e32 v123, v123, v95
	v_add_f32_e32 v122, v122, v96
	v_add_f32_e32 v123, v123, v97
	v_add_f32_e32 v122, v122, v98
	v_add_f32_e32 v123, v123, v99
	v_add_f32_e32 v122, v122, v100
	v_add_f32_e32 v123, v123, v101
	v_cvt_pk_bf16_f32 v234, v94, v95
	v_cvt_pk_bf16_f32 v235, v96, v97
	v_cvt_pk_bf16_f32 v236, v98, v99
	v_cvt_pk_bf16_f32 v237, v100, v101
	v_sub_f32_e32 v102, v102, v160
	v_sub_f32_e32 v103, v103, v160
	v_sub_f32_e32 v104, v104, v160
	v_sub_f32_e32 v105, v105, v160
	v_sub_f32_e32 v106, v106, v160
	v_sub_f32_e32 v107, v107, v160
	v_sub_f32_e32 v108, v108, v160
	v_sub_f32_e32 v109, v109, v160
	v_exp_f32_e32 v102, v102
	v_exp_f32_e32 v103, v103
	v_exp_f32_e32 v104, v104
	v_exp_f32_e32 v105, v105
	v_exp_f32_e32 v106, v106
	v_exp_f32_e32 v107, v107
	v_exp_f32_e32 v108, v108
	v_exp_f32_e32 v109, v109
	v_add_f32_e32 v122, v122, v102
	v_add_f32_e32 v123, v123, v103
	v_add_f32_e32 v122, v122, v104
	v_add_f32_e32 v123, v123, v105
	v_add_f32_e32 v122, v122, v106
	v_add_f32_e32 v123, v123, v107
	v_add_f32_e32 v122, v122, v108
	v_add_f32_e32 v123, v123, v109
	v_cvt_pk_bf16_f32 v238, v102, v103
	v_cvt_pk_bf16_f32 v239, v104, v105
	v_cvt_pk_bf16_f32 v240, v106, v107
	v_cvt_pk_bf16_f32 v241, v108, v109
	v_add_f32_e32 v122, v122, v123
	v_add_f32_e32 v161, v161, v122
	s_waitcnt lgkmcnt(8)
	ds_read_b64_tr_b16 v[222:223], v159 offset:41984
	ds_read_b64_tr_b16 v[224:225], v159 offset:42496
	s_waitcnt vmcnt(0)
	s_and_saveexec_b64 s[12:13], s[6:7]
	s_cbranch_execz .Lf3_nocwt3CONLY
	v_xor_b32_e32 v152, 0x80000000, v152
	ds_write_b32 v154, v152 offset:43264
.Lf3_nocwt3CONLY:
	s_or_b64 exec, exec, s[12:13]
	s_waitcnt lgkmcnt(0)
	s_barrier
	v_mfma_f32_32x32x16_bf16 v[14:29], v[190:193], v[226:229], v[14:29]
	v_mfma_f32_32x32x16_bf16 v[30:45], v[194:197], v[226:229], v[30:45]
	s_mov_b32 m0, s55
	s_nop 0
	global_load_lds_dwordx4 v[248:249], off
	v_mfma_f32_32x32x16_bf16 v[14:29], v[198:201], v[230:233], v[14:29]
	v_mfma_f32_32x32x16_bf16 v[30:45], v[202:205], v[230:233], v[30:45]
	v_mfma_f32_32x32x16_bf16 v[14:29], v[206:209], v[234:237], v[14:29]
	v_mfma_f32_32x32x16_bf16 v[30:45], v[210:213], v[234:237], v[30:45]
	v_mfma_f32_32x32x16_bf16 v[14:29], v[214:217], v[238:241], v[14:29]
	v_mfma_f32_32x32x16_bf16 v[30:45], v[222:225], v[238:241], v[30:45]
	v_lshl_add_u64 v[244:245], v[244:245], 0, s[46:47]
	v_lshl_add_u64 v[116:117], v[116:117], 0, s[46:47]
	v_lshl_add_u64 v[248:249], v[248:249], 0, s[46:47]
	v_lshl_add_u64 v[250:251], v[250:251], 0, s[48:49]
.Lf3_tail4:
	s_cmp_eq_u32 s11, 3
	s_cbranch_scc1 .Lf3_t4_FULLM
	s_cmp_eq_u32 s11, 2
	s_cbranch_scc1 .Lf3_t4_CONLY
	s_waitcnt lgkmcnt(0)
	s_waitcnt vmcnt(0)
	s_waitcnt lgkmcnt(0)
	s_barrier
	v_lshl_add_u64 v[242:243], v[242:243], 0, s[46:47]
	v_lshl_add_u64 v[114:115], v[114:115], 0, s[46:47]
	v_lshl_add_u64 v[246:247], v[246:247], 0, s[46:47]
	s_branch .Lf3_tail5

.Lf3_resc_rett4FULLM:
	s_waitcnt lgkmcnt(7)
	v_mfma_f32_32x32x16_bf16 v[78:93], v[190:193], v[0:3], v[78:93]
	ds_read_b64_tr_b16 v[190:191], v159 offset:26624
	ds_read_b64_tr_b16 v[192:193], v159 offset:27136
	v_sub_f32_e32 v46, v46, v160
	v_sub_f32_e32 v47, v47, v160
	v_sub_f32_e32 v48, v48, v160
	v_sub_f32_e32 v49, v49, v160
	v_sub_f32_e32 v50, v50, v160
	v_sub_f32_e32 v51, v51, v160
	v_sub_f32_e32 v52, v52, v160
	v_sub_f32_e32 v53, v53, v160
	v_exp_f32_e32 v46, v46
	v_exp_f32_e32 v47, v47
	v_exp_f32_e32 v48, v48
	v_exp_f32_e32 v49, v49
	s_waitcnt lgkmcnt(8)
	v_mfma_f32_32x32x16_bf16 v[94:109], v[194:197], v[0:3], v[94:109]
	ds_read_b64_tr_b16 v[194:195], v159 offset:30720
	ds_read_b64_tr_b16 v[196:197], v159 offset:31232
	v_exp_f32_e32 v50, v50
	v_exp_f32_e32 v51, v51
	v_exp_f32_e32 v52, v52
	v_exp_f32_e32 v53, v53
	v_add_f32_e32 v122, v46, v47
	v_add_f32_e32 v123, v48, v49
	v_add_f32_e32 v122, v122, v50
	v_add_f32_e32 v123, v123, v51
	v_add_f32_e32 v122, v122, v52
	v_add_f32_e32 v123, v123, v53
	v_cvt_pk_bf16_f32 v226, v46, v47
	v_cvt_pk_bf16_f32 v227, v48, v49
	s_waitcnt lgkmcnt(9)
	v_mfma_f32_32x32x16_bf16 v[78:93], v[198:201], v[4:7], v[78:93]
	ds_read_b64_tr_b16 v[198:199], v159 offset:27648
	ds_read_b64_tr_b16 v[200:201], v159 offset:28160
	v_cvt_pk_bf16_f32 v228, v50, v51
	v_cvt_pk_bf16_f32 v229, v52, v53
	v_sub_f32_e32 v54, v54, v160
	v_sub_f32_e32 v55, v55, v160
	v_sub_f32_e32 v56, v56, v160
	v_sub_f32_e32 v57, v57, v160
	v_sub_f32_e32 v58, v58, v160
	v_sub_f32_e32 v59, v59, v160
	v_sub_f32_e32 v60, v60, v160
	v_sub_f32_e32 v61, v61, v160
	v_exp_f32_e32 v54, v54
	s_waitcnt lgkmcnt(10)
	v_mfma_f32_32x32x16_bf16 v[94:109], v[202:205], v[4:7], v[94:109]
	ds_read_b64_tr_b16 v[202:203], v159 offset:31744
	ds_read_b64_tr_b16 v[204:205], v159 offset:32256
	v_exp_f32_e32 v55, v55
	v_exp_f32_e32 v56, v56
	v_exp_f32_e32 v57, v57
	v_exp_f32_e32 v58, v58
	v_exp_f32_e32 v59, v59
	v_exp_f32_e32 v60, v60
	v_exp_f32_e32 v61, v61
	v_add_f32_e32 v122, v122, v54
	v_add_f32_e32 v123, v123, v55
	v_add_f32_e32 v122, v122, v56
	v_add_f32_e32 v123, v123, v57
	s_waitcnt lgkmcnt(11)
	v_mfma_f32_32x32x16_bf16 v[78:93], v[206:209], v[8:11], v[78:93]
	ds_read_b64_tr_b16 v[206:207], v159 offset:28672
	ds_read_b64_tr_b16 v[208:209], v159 offset:29184
	v_add_f32_e32 v122, v122, v58
	v_add_f32_e32 v123, v123, v59
	v_add_f32_e32 v122, v122, v60
	v_add_f32_e32 v123, v123, v61
	v_cvt_pk_bf16_f32 v230, v54, v55
	v_cvt_pk_bf16_f32 v231, v56, v57
	v_cvt_pk_bf16_f32 v232, v58, v59
	v_cvt_pk_bf16_f32 v233, v60, v61
	v_sub_f32_e32 v62, v62, v160
	v_sub_f32_e32 v63, v63, v160
	v_sub_f32_e32 v64, v64, v160
	s_waitcnt lgkmcnt(12)
	v_mfma_f32_32x32x16_bf16 v[94:109], v[210:213], v[8:11], v[94:109]
	ds_read_b64_tr_b16 v[210:211], v159 offset:32768
	ds_read_b64_tr_b16 v[212:213], v159 offset:33280
	v_sub_f32_e32 v65, v65, v160
	v_sub_f32_e32 v66, v66, v160
	v_sub_f32_e32 v67, v67, v160
	v_sub_f32_e32 v68, v68, v160
	v_sub_f32_e32 v69, v69, v160
	v_exp_f32_e32 v62, v62
	v_exp_f32_e32 v63, v63
	v_exp_f32_e32 v64, v64
	v_exp_f32_e32 v65, v65
	v_exp_f32_e32 v66, v66
	v_exp_f32_e32 v67, v67
	s_waitcnt lgkmcnt(13)
	v_mfma_f32_32x32x16_bf16 v[78:93], v[214:217], v[110:113], v[78:93]
	ds_read_b64_tr_b16 v[214:215], v159 offset:29696
	ds_read_b64_tr_b16 v[216:217], v159 offset:30208
	v_exp_f32_e32 v68, v68
	v_exp_f32_e32 v69, v69
	v_add_f32_e32 v122, v122, v62
	v_add_f32_e32 v123, v123, v63
	v_add_f32_e32 v122, v122, v64
	v_add_f32_e32 v123, v123, v65
	v_add_f32_e32 v122, v122, v66
	v_add_f32_e32 v123, v123, v67
	v_add_f32_e32 v122, v122, v68
	v_add_f32_e32 v123, v123, v69
	v_cvt_pk_bf16_f32 v234, v62, v63
	s_waitcnt lgkmcnt(14)
	v_mfma_f32_32x32x16_bf16 v[94:109], v[222:225], v[110:113], v[94:109]
	s_waitcnt lgkmcnt(13)
	ds_read_b64_tr_b16 v[222:223], v159 offset:33792
	ds_read_b64_tr_b16 v[224:225], v159 offset:34304
	v_cvt_pk_bf16_f32 v235, v64, v65
	v_cvt_pk_bf16_f32 v236, v66, v67
	v_cvt_pk_bf16_f32 v237, v68, v69
	v_sub_f32_e32 v70, v70, v160
	v_sub_f32_e32 v71, v71, v160
	v_sub_f32_e32 v72, v72, v160
	v_sub_f32_e32 v73, v73, v160
	v_sub_f32_e32 v74, v74, v160
	v_sub_f32_e32 v75, v75, v160
	v_sub_f32_e32 v76, v76, v160
	v_sub_f32_e32 v77, v77, v160
	s_waitcnt lgkmcnt(8)
	s_waitcnt vmcnt(0)
	v_exp_f32_e32 v70, v70
	v_exp_f32_e32 v71, v71
	v_exp_f32_e32 v72, v72
	v_exp_f32_e32 v73, v73
	v_exp_f32_e32 v74, v74
	v_exp_f32_e32 v75, v75
	v_exp_f32_e32 v76, v76
	v_exp_f32_e32 v77, v77
	v_add_f32_e32 v122, v122, v70
	v_add_f32_e32 v123, v123, v71
	v_add_f32_e32 v122, v122, v72
	v_add_f32_e32 v123, v123, v73
	v_add_f32_e32 v122, v122, v74
	v_add_f32_e32 v123, v123, v75
	v_add_f32_e32 v122, v122, v76
	v_add_f32_e32 v123, v123, v77
	v_cvt_pk_bf16_f32 v238, v70, v71
	v_cvt_pk_bf16_f32 v239, v72, v73
	v_cvt_pk_bf16_f32 v240, v74, v75
	v_cvt_pk_bf16_f32 v241, v76, v77
	v_add_f32_e32 v122, v122, v123
	v_add_f32_e32 v161, v161, v122
	s_waitcnt lgkmcnt(0)
	s_barrier
	ds_read_b128 v[46:49], v158 offset:43008
	ds_read_b128 v[50:53], v158 offset:43040
	ds_read_b128 v[54:57], v158 offset:43072
	ds_read_b128 v[58:61], v158 offset:43104
	ds_read_b128 v[62:65], v158 offset:43136
	ds_read_b128 v[66:69], v158 offset:43168
	ds_read_b128 v[70:73], v158 offset:43200
	ds_read_b128 v[74:77], v158 offset:43232
	v_mfma_f32_32x32x16_bf16 v[14:29], v[190:193], v[226:229], v[14:29]
	ds_read_b128 v[190:193], v218
	v_cmp_le_i32_e64 s[52:53], 0, v219
	v_cmp_le_i32_e64 s[14:15], 32, v219
	v_cmp_le_i32_e64 s[16:17], 1, v219
	v_cndmask_b32_e64 v78, v220, v78, s[52:53]
	v_cmp_le_i32_e64 s[52:53], 33, v219
	v_cndmask_b32_e64 v94, v220, v94, s[14:15]
	v_cmp_le_i32_e64 s[14:15], 2, v219
	v_cndmask_b32_e64 v79, v220, v79, s[16:17]
	v_cmp_le_i32_e64 s[16:17], 34, v219
	v_cndmask_b32_e64 v95, v220, v95, s[52:53]
	v_cmp_le_i32_e64 s[52:53], 3, v219
	v_mfma_f32_32x32x16_bf16 v[30:45], v[194:197], v[226:229], v[30:45]
	ds_read_b128 v[194:197], v218 offset:4608
	v_cndmask_b32_e64 v80, v220, v80, s[14:15]
	v_cmp_le_i32_e64 s[14:15], 35, v219
	v_cndmask_b32_e64 v96, v220, v96, s[16:17]
	v_cmp_le_i32_e64 s[16:17], 8, v219
	v_cndmask_b32_e64 v81, v220, v81, s[52:53]
	v_cmp_le_i32_e64 s[52:53], 40, v219
	v_cndmask_b32_e64 v97, v220, v97, s[14:15]
	v_cmp_le_i32_e64 s[14:15], 9, v219
	v_cndmask_b32_e64 v82, v220, v82, s[16:17]
	v_cmp_le_i32_e64 s[16:17], 41, v219
	v_cndmask_b32_e64 v98, v220, v98, s[52:53]
	v_mfma_f32_32x32x16_bf16 v[14:29], v[198:201], v[230:233], v[14:29]
	ds_read_b128 v[198:201], v218 offset:32
	v_cmp_le_i32_e64 s[52:53], 10, v219
	v_cndmask_b32_e64 v83, v220, v83, s[14:15]
	v_cmp_le_i32_e64 s[14:15], 42, v219
	v_cndmask_b32_e64 v99, v220, v99, s[16:17]
	v_cmp_le_i32_e64 s[16:17], 11, v219
	v_cndmask_b32_e64 v84, v220, v84, s[52:53]
	v_cmp_le_i32_e64 s[52:53], 43, v219
	v_cndmask_b32_e64 v100, v220, v100, s[14:15]
	v_cmp_le_i32_e64 s[14:15], 16, v219
	v_cndmask_b32_e64 v85, v220, v85, s[16:17]
	v_cmp_le_i32_e64 s[16:17], 48, v219
	v_mfma_f32_32x32x16_bf16 v[30:45], v[202:205], v[230:233], v[30:45]
	ds_read_b128 v[202:205], v218 offset:4640
	v_cndmask_b32_e64 v101, v220, v101, s[52:53]
	v_cmp_le_i32_e64 s[52:53], 17, v219
	v_cndmask_b32_e64 v86, v220, v86, s[14:15]
	v_cmp_le_i32_e64 s[14:15], 49, v219
	v_cndmask_b32_e64 v102, v220, v102, s[16:17]
	v_cmp_le_i32_e64 s[16:17], 18, v219
	v_cndmask_b32_e64 v87, v220, v87, s[52:53]
	v_cmp_le_i32_e64 s[52:53], 50, v219
	v_cndmask_b32_e64 v103, v220, v103, s[14:15]
	v_cmp_le_i32_e64 s[14:15], 19, v219
	v_cndmask_b32_e64 v88, v220, v88, s[16:17]
	v_mfma_f32_32x32x16_bf16 v[14:29], v[206:209], v[234:237], v[14:29]
	ds_read_b128 v[206:209], v218 offset:64
	v_cmp_le_i32_e64 s[16:17], 51, v219
	v_cndmask_b32_e64 v104, v220, v104, s[52:53]
	v_cmp_le_i32_e64 s[52:53], 24, v219
	v_cndmask_b32_e64 v89, v220, v89, s[14:15]
	v_cmp_le_i32_e64 s[14:15], 56, v219
	v_cndmask_b32_e64 v105, v220, v105, s[16:17]
	v_cmp_le_i32_e64 s[16:17], 25, v219
	v_cndmask_b32_e64 v90, v220, v90, s[52:53]
	v_cmp_le_i32_e64 s[52:53], 57, v219
	v_cndmask_b32_e64 v106, v220, v106, s[14:15]
	v_mfma_f32_32x32x16_bf16 v[30:45], v[210:213], v[234:237], v[30:45]
	ds_read_b128 v[210:213], v218 offset:4672
	v_cmp_le_i32_e64 s[14:15], 26, v219
	v_cndmask_b32_e64 v91, v220, v91, s[16:17]
	v_cmp_le_i32_e64 s[16:17], 58, v219
	v_cndmask_b32_e64 v107, v220, v107, s[52:53]
	v_cmp_le_i32_e64 s[52:53], 27, v219
	v_cndmask_b32_e64 v92, v220, v92, s[14:15]
	v_cmp_le_i32_e64 s[14:15], 59, v219
	v_cndmask_b32_e64 v108, v220, v108, s[16:17]
	v_cndmask_b32_e64 v93, v220, v93, s[52:53]
	v_cndmask_b32_e64 v109, v220, v109, s[14:15]
	v_mfma_f32_32x32x16_bf16 v[14:29], v[214:217], v[238:241], v[14:29]
	ds_read_b128 v[214:217], v218 offset:96
	v_max3_f32 v124, v78, v79, v80
	v_max3_f32 v125, v81, v82, v83
	v_max3_f32 v124, v124, v84, v85
	v_max3_f32 v125, v125, v86, v87
	v_max3_f32 v124, v124, v88, v89
	v_max3_f32 v125, v125, v90, v91
	v_max3_f32 v124, v124, v92, v93
	v_max3_f32 v125, v125, v94, v95
	v_max3_f32 v124, v124, v96, v97
	v_max3_f32 v125, v125, v98, v99
	v_mfma_f32_32x32x16_bf16 v[30:45], v[222:225], v[238:241], v[30:45]
	s_waitcnt lgkmcnt(14)
	ds_read_b128 v[222:225], v218 offset:4704
	v_max3_f32 v124, v124, v100, v101
	v_max3_f32 v125, v125, v102, v103
	v_max3_f32 v124, v124, v104, v105
	v_max3_f32 v125, v125, v106, v107
	v_max3_f32 v124, v124, v108, v109
	v_max_f32_e32 v124, v124, v125
	v_mov_b32_e32 v125, v124
	s_nop 1
	v_permlane32_swap_b32_e32 v124, v125
	v_max_f32_e32 v126, v124, v125
	v_lshl_add_u64 v[242:243], v[242:243], 0, s[46:47]
	v_lshl_add_u64 v[114:115], v[114:115], 0, s[46:47]
	v_lshl_add_u64 v[246:247], v[246:247], 0, s[46:47]
	s_branch .Lf3_tail5

.Lf3_resc_rett4CONLY:
	s_waitcnt lgkmcnt(0)
	ds_read_b64_tr_b16 v[190:191], v159 offset:26624
	ds_read_b64_tr_b16 v[192:193], v159 offset:27136
	ds_read_b64_tr_b16 v[194:195], v159 offset:30720
	ds_read_b64_tr_b16 v[196:197], v159 offset:31232
	ds_read_b64_tr_b16 v[198:199], v159 offset:27648
	ds_read_b64_tr_b16 v[200:201], v159 offset:28160
	ds_read_b64_tr_b16 v[202:203], v159 offset:31744
	ds_read_b64_tr_b16 v[204:205], v159 offset:32256
	ds_read_b64_tr_b16 v[206:207], v159 offset:28672
	ds_read_b64_tr_b16 v[208:209], v159 offset:29184
	ds_read_b64_tr_b16 v[210:211], v159 offset:32768
	ds_read_b64_tr_b16 v[212:213], v159 offset:33280
	ds_read_b64_tr_b16 v[214:215], v159 offset:29696
	ds_read_b64_tr_b16 v[216:217], v159 offset:30208
	v_sub_f32_e32 v46, v46, v160
	v_sub_f32_e32 v47, v47, v160
	v_sub_f32_e32 v48, v48, v160
	v_sub_f32_e32 v49, v49, v160
	v_sub_f32_e32 v50, v50, v160
	v_sub_f32_e32 v51, v51, v160
	v_sub_f32_e32 v52, v52, v160
	v_sub_f32_e32 v53, v53, v160
	v_exp_f32_e32 v46, v46
	v_exp_f32_e32 v47, v47
	v_exp_f32_e32 v48, v48
	v_exp_f32_e32 v49, v49
	v_exp_f32_e32 v50, v50
	v_exp_f32_e32 v51, v51
	v_exp_f32_e32 v52, v52
	v_exp_f32_e32 v53, v53
	v_add_f32_e32 v122, v46, v47
	v_add_f32_e32 v123, v48, v49
	v_add_f32_e32 v122, v122, v50
	v_add_f32_e32 v123, v123, v51
	v_add_f32_e32 v122, v122, v52
	v_add_f32_e32 v123, v123, v53
	v_cvt_pk_bf16_f32 v226, v46, v47
	v_cvt_pk_bf16_f32 v227, v48, v49
	v_cvt_pk_bf16_f32 v228, v50, v51
	v_cvt_pk_bf16_f32 v229, v52, v53
	v_sub_f32_e32 v54, v54, v160
	v_sub_f32_e32 v55, v55, v160
	v_sub_f32_e32 v56, v56, v160
	v_sub_f32_e32 v57, v57, v160
	v_sub_f32_e32 v58, v58, v160
	v_sub_f32_e32 v59, v59, v160
	v_sub_f32_e32 v60, v60, v160
	v_sub_f32_e32 v61, v61, v160
	v_exp_f32_e32 v54, v54
	v_exp_f32_e32 v55, v55
	v_exp_f32_e32 v56, v56
	v_exp_f32_e32 v57, v57
	v_exp_f32_e32 v58, v58
	v_exp_f32_e32 v59, v59
	v_exp_f32_e32 v60, v60
	v_exp_f32_e32 v61, v61
	v_add_f32_e32 v122, v122, v54
	v_add_f32_e32 v123, v123, v55
	v_add_f32_e32 v122, v122, v56
	v_add_f32_e32 v123, v123, v57
	v_add_f32_e32 v122, v122, v58
	v_add_f32_e32 v123, v123, v59
	v_add_f32_e32 v122, v122, v60
	v_add_f32_e32 v123, v123, v61
	v_cvt_pk_bf16_f32 v230, v54, v55
	v_cvt_pk_bf16_f32 v231, v56, v57
	v_cvt_pk_bf16_f32 v232, v58, v59
	v_cvt_pk_bf16_f32 v233, v60, v61
	v_sub_f32_e32 v62, v62, v160
	v_sub_f32_e32 v63, v63, v160
	v_sub_f32_e32 v64, v64, v160
	v_sub_f32_e32 v65, v65, v160
	v_sub_f32_e32 v66, v66, v160
	v_sub_f32_e32 v67, v67, v160
	v_sub_f32_e32 v68, v68, v160
	v_sub_f32_e32 v69, v69, v160
	v_exp_f32_e32 v62, v62
	v_exp_f32_e32 v63, v63
	v_exp_f32_e32 v64, v64
	v_exp_f32_e32 v65, v65
	v_exp_f32_e32 v66, v66
	v_exp_f32_e32 v67, v67
	v_exp_f32_e32 v68, v68
	v_exp_f32_e32 v69, v69
	v_add_f32_e32 v122, v122, v62
	v_add_f32_e32 v123, v123, v63
	v_add_f32_e32 v122, v122, v64
	v_add_f32_e32 v123, v123, v65
	v_add_f32_e32 v122, v122, v66
	v_add_f32_e32 v123, v123, v67
	v_add_f32_e32 v122, v122, v68
	v_add_f32_e32 v123, v123, v69
	v_cvt_pk_bf16_f32 v234, v62, v63
	v_cvt_pk_bf16_f32 v235, v64, v65
	v_cvt_pk_bf16_f32 v236, v66, v67
	v_cvt_pk_bf16_f32 v237, v68, v69
	v_sub_f32_e32 v70, v70, v160
	v_sub_f32_e32 v71, v71, v160
	v_sub_f32_e32 v72, v72, v160
	v_sub_f32_e32 v73, v73, v160
	v_sub_f32_e32 v74, v74, v160
	v_sub_f32_e32 v75, v75, v160
	v_sub_f32_e32 v76, v76, v160
	v_sub_f32_e32 v77, v77, v160
	v_exp_f32_e32 v70, v70
	v_exp_f32_e32 v71, v71
	v_exp_f32_e32 v72, v72
	v_exp_f32_e32 v73, v73
	v_exp_f32_e32 v74, v74
	v_exp_f32_e32 v75, v75
	v_exp_f32_e32 v76, v76
	v_exp_f32_e32 v77, v77
	v_add_f32_e32 v122, v122, v70
	v_add_f32_e32 v123, v123, v71
	v_add_f32_e32 v122, v122, v72
	v_add_f32_e32 v123, v123, v73
	v_add_f32_e32 v122, v122, v74
	v_add_f32_e32 v123, v123, v75
	v_add_f32_e32 v122, v122, v76
	v_add_f32_e32 v123, v123, v77
	v_cvt_pk_bf16_f32 v238, v70, v71
	v_cvt_pk_bf16_f32 v239, v72, v73
	v_cvt_pk_bf16_f32 v240, v74, v75
	v_cvt_pk_bf16_f32 v241, v76, v77
	v_add_f32_e32 v122, v122, v123
	v_add_f32_e32 v161, v161, v122
	s_waitcnt lgkmcnt(8)
	ds_read_b64_tr_b16 v[222:223], v159 offset:33792
	ds_read_b64_tr_b16 v[224:225], v159 offset:34304
	s_waitcnt vmcnt(0)
	s_waitcnt lgkmcnt(0)
	s_barrier
	v_mfma_f32_32x32x16_bf16 v[14:29], v[190:193], v[226:229], v[14:29]
	v_mfma_f32_32x32x16_bf16 v[30:45], v[194:197], v[226:229], v[30:45]
	v_mfma_f32_32x32x16_bf16 v[14:29], v[198:201], v[230:233], v[14:29]
	v_mfma_f32_32x32x16_bf16 v[30:45], v[202:205], v[230:233], v[30:45]
	v_mfma_f32_32x32x16_bf16 v[14:29], v[206:209], v[234:237], v[14:29]
	v_mfma_f32_32x32x16_bf16 v[30:45], v[210:213], v[234:237], v[30:45]
	v_mfma_f32_32x32x16_bf16 v[14:29], v[214:217], v[238:241], v[14:29]
	v_mfma_f32_32x32x16_bf16 v[30:45], v[222:225], v[238:241], v[30:45]
	v_lshl_add_u64 v[242:243], v[242:243], 0, s[46:47]
	v_lshl_add_u64 v[114:115], v[114:115], 0, s[46:47]
	v_lshl_add_u64 v[246:247], v[246:247], 0, s[46:47]
.Lf3_tail5:
	s_cmp_eq_u32 s11, 3
	s_cbranch_scc1 .Lf3_t5_CONLY
	s_waitcnt lgkmcnt(0)
	s_waitcnt lgkmcnt(0)
	s_barrier
	v_lshl_add_u64 v[244:245], v[244:245], 0, s[46:47]
	v_lshl_add_u64 v[116:117], v[116:117], 0, s[46:47]
	v_lshl_add_u64 v[248:249], v[248:249], 0, s[46:47]
	v_lshl_add_u64 v[250:251], v[250:251], 0, s[48:49]
	s_branch .Lf3_done

.Lf3_resc_rett5CONLY:
	s_waitcnt lgkmcnt(0)
	ds_read_b64_tr_b16 v[190:191], v159 offset:34816
	ds_read_b64_tr_b16 v[192:193], v159 offset:35328
	ds_read_b64_tr_b16 v[194:195], v159 offset:38912
	ds_read_b64_tr_b16 v[196:197], v159 offset:39424
	ds_read_b64_tr_b16 v[198:199], v159 offset:35840
	ds_read_b64_tr_b16 v[200:201], v159 offset:36352
	ds_read_b64_tr_b16 v[202:203], v159 offset:39936
	ds_read_b64_tr_b16 v[204:205], v159 offset:40448
	ds_read_b64_tr_b16 v[206:207], v159 offset:36864
	ds_read_b64_tr_b16 v[208:209], v159 offset:37376
	ds_read_b64_tr_b16 v[210:211], v159 offset:40960
	ds_read_b64_tr_b16 v[212:213], v159 offset:41472
	ds_read_b64_tr_b16 v[214:215], v159 offset:37888
	ds_read_b64_tr_b16 v[216:217], v159 offset:38400
	v_sub_f32_e32 v78, v78, v160
	v_sub_f32_e32 v79, v79, v160
	v_sub_f32_e32 v80, v80, v160
	v_sub_f32_e32 v81, v81, v160
	v_sub_f32_e32 v82, v82, v160
	v_sub_f32_e32 v83, v83, v160
	v_sub_f32_e32 v84, v84, v160
	v_sub_f32_e32 v85, v85, v160
	v_exp_f32_e32 v78, v78
	v_exp_f32_e32 v79, v79
	v_exp_f32_e32 v80, v80
	v_exp_f32_e32 v81, v81
	v_exp_f32_e32 v82, v82
	v_exp_f32_e32 v83, v83
	v_exp_f32_e32 v84, v84
	v_exp_f32_e32 v85, v85
	v_add_f32_e32 v122, v78, v79
	v_add_f32_e32 v123, v80, v81
	v_add_f32_e32 v122, v122, v82
	v_add_f32_e32 v123, v123, v83
	v_add_f32_e32 v122, v122, v84
	v_add_f32_e32 v123, v123, v85
	v_cvt_pk_bf16_f32 v226, v78, v79
	v_cvt_pk_bf16_f32 v227, v80, v81
	v_cvt_pk_bf16_f32 v228, v82, v83
	v_cvt_pk_bf16_f32 v229, v84, v85
	v_sub_f32_e32 v86, v86, v160
	v_sub_f32_e32 v87, v87, v160
	v_sub_f32_e32 v88, v88, v160
	v_sub_f32_e32 v89, v89, v160
	v_sub_f32_e32 v90, v90, v160
	v_sub_f32_e32 v91, v91, v160
	v_sub_f32_e32 v92, v92, v160
	v_sub_f32_e32 v93, v93, v160
	v_exp_f32_e32 v86, v86
	v_exp_f32_e32 v87, v87
	v_exp_f32_e32 v88, v88
	v_exp_f32_e32 v89, v89
	v_exp_f32_e32 v90, v90
	v_exp_f32_e32 v91, v91
	v_exp_f32_e32 v92, v92
	v_exp_f32_e32 v93, v93
	v_add_f32_e32 v122, v122, v86
	v_add_f32_e32 v123, v123, v87
	v_add_f32_e32 v122, v122, v88
	v_add_f32_e32 v123, v123, v89
	v_add_f32_e32 v122, v122, v90
	v_add_f32_e32 v123, v123, v91
	v_add_f32_e32 v122, v122, v92
	v_add_f32_e32 v123, v123, v93
	v_cvt_pk_bf16_f32 v230, v86, v87
	v_cvt_pk_bf16_f32 v231, v88, v89
	v_cvt_pk_bf16_f32 v232, v90, v91
	v_cvt_pk_bf16_f32 v233, v92, v93
	v_sub_f32_e32 v94, v94, v160
	v_sub_f32_e32 v95, v95, v160
	v_sub_f32_e32 v96, v96, v160
	v_sub_f32_e32 v97, v97, v160
	v_sub_f32_e32 v98, v98, v160
	v_sub_f32_e32 v99, v99, v160
	v_sub_f32_e32 v100, v100, v160
	v_sub_f32_e32 v101, v101, v160
	v_exp_f32_e32 v94, v94
	v_exp_f32_e32 v95, v95
	v_exp_f32_e32 v96, v96
	v_exp_f32_e32 v97, v97
	v_exp_f32_e32 v98, v98
	v_exp_f32_e32 v99, v99
	v_exp_f32_e32 v100, v100
	v_exp_f32_e32 v101, v101
	v_add_f32_e32 v122, v122, v94
	v_add_f32_e32 v123, v123, v95
	v_add_f32_e32 v122, v122, v96
	v_add_f32_e32 v123, v123, v97
	v_add_f32_e32 v122, v122, v98
	v_add_f32_e32 v123, v123, v99
	v_add_f32_e32 v122, v122, v100
	v_add_f32_e32 v123, v123, v101
	v_cvt_pk_bf16_f32 v234, v94, v95
	v_cvt_pk_bf16_f32 v235, v96, v97
	v_cvt_pk_bf16_f32 v236, v98, v99
	v_cvt_pk_bf16_f32 v237, v100, v101
	v_sub_f32_e32 v102, v102, v160
	v_sub_f32_e32 v103, v103, v160
	v_sub_f32_e32 v104, v104, v160
	v_sub_f32_e32 v105, v105, v160
	v_sub_f32_e32 v106, v106, v160
	v_sub_f32_e32 v107, v107, v160
	v_sub_f32_e32 v108, v108, v160
	v_sub_f32_e32 v109, v109, v160
	v_exp_f32_e32 v102, v102
	v_exp_f32_e32 v103, v103
	v_exp_f32_e32 v104, v104
	v_exp_f32_e32 v105, v105
	v_exp_f32_e32 v106, v106
	v_exp_f32_e32 v107, v107
	v_exp_f32_e32 v108, v108
	v_exp_f32_e32 v109, v109
	v_add_f32_e32 v122, v122, v102
	v_add_f32_e32 v123, v123, v103
	v_add_f32_e32 v122, v122, v104
	v_add_f32_e32 v123, v123, v105
	v_add_f32_e32 v122, v122, v106
	v_add_f32_e32 v123, v123, v107
	v_add_f32_e32 v122, v122, v108
	v_add_f32_e32 v123, v123, v109
	v_cvt_pk_bf16_f32 v238, v102, v103
	v_cvt_pk_bf16_f32 v239, v104, v105
	v_cvt_pk_bf16_f32 v240, v106, v107
	v_cvt_pk_bf16_f32 v241, v108, v109
	v_add_f32_e32 v122, v122, v123
	v_add_f32_e32 v161, v161, v122
	s_waitcnt lgkmcnt(8)
	ds_read_b64_tr_b16 v[222:223], v159 offset:41984
	ds_read_b64_tr_b16 v[224:225], v159 offset:42496
	s_waitcnt lgkmcnt(0)
	s_barrier
	v_mfma_f32_32x32x16_bf16 v[14:29], v[190:193], v[226:229], v[14:29]
	v_mfma_f32_32x32x16_bf16 v[30:45], v[194:197], v[226:229], v[30:45]
	v_mfma_f32_32x32x16_bf16 v[14:29], v[198:201], v[230:233], v[14:29]
	v_mfma_f32_32x32x16_bf16 v[30:45], v[202:205], v[230:233], v[30:45]
	v_mfma_f32_32x32x16_bf16 v[14:29], v[206:209], v[234:237], v[14:29]
	v_mfma_f32_32x32x16_bf16 v[30:45], v[210:213], v[234:237], v[30:45]
	v_mfma_f32_32x32x16_bf16 v[14:29], v[214:217], v[238:241], v[14:29]
	v_mfma_f32_32x32x16_bf16 v[30:45], v[222:225], v[238:241], v[30:45]
	v_lshl_add_u64 v[244:245], v[244:245], 0, s[46:47]
	v_lshl_add_u64 v[116:117], v[116:117], 0, s[46:47]
	v_lshl_add_u64 v[248:249], v[248:249], 0, s[46:47]
	v_lshl_add_u64 v[250:251], v[250:251], 0, s[48:49]
